# removed per-MMA-block s_setprio flips from all six GEMM K-loops (on top of 4-row streaming loops + Q-load)
# baseline (speedup 1.0000x reference)
; #define PG8_STAGE(bufoff, gbase, voff) do { _Pragma("unroll") for (int _i = 0; _i < 2; ++_i) \
;         __builtin_amdgcn_global_load_lds((const unsigned*)((const char*)(gbase) + (voff)[_i]), (PG8_LAS unsigned*)(lds + (bufoff) + ldsw + _i * 8192), 16, 0, 0); } while (0)
; #define PG8_LDA(dst, b, h) do { _Pragma("unroll") for (int m = 0; m < 4; ++m) _Pragma("unroll") for (int k = 0; k < 2; ++k) dst[m][k] = *(const PG8_LAS bf16x8*)(lds + PG8_SA(b, h) + aoff + m * 2048 + k * 1024); } while (0)
; #define PG8_LDB(dst, b, h) do { _Pragma("unroll") for (int n = 0; n < 2; ++n) _Pragma("unroll") for (int k = 0; k < 2; ++k) dst[n][k] = *(const PG8_LAS bf16x8*)(lds + PG8_SB(b, h) + boff + n * 2048 + k * 1024); } while (0)
; #define PG8_MMA(ai, bj, At, Bt) do { __builtin_amdgcn_s_setprio(1); _Pragma("unroll") for (int m = 0; m < 4; ++m) _Pragma("unroll") for (int n = 0; n < 2; ++n) _Pragma("unroll") for (int k = 0; k < 2; ++k) \
;         acc[ai][bj][m][n] = __builtin_amdgcn_mfma_f32_16x16x32_bf16(Bt[n][k], At[m][k], acc[ai][bj][m][n], 0, 0, 0); __builtin_amdgcn_s_setprio(0); } while (0)
; #define PG8_WAIT_V(n) asm volatile("s_waitcnt vmcnt(" #n ")" ::: "memory")
; #define PG8_BAR __builtin_amdgcn_s_barrier()
; template <class Epi, class Sched, bool ALIGN_EPI = false, bool SP2 = false>
; __device__ __forceinline__ void gemm_phase(PG8_LAS unsigned char* lds, const Gemm g, const Sched& S, const Epi& E) {
;     ...
;         for (int t = 0; t < nt_u; t += 2) {
;             const bool last = (t == nt_u - 2);
;             const char* a1 = cA + (size_t)(t + 1) * kstep;
;             const char* a2 = last ? nA : cA + (size_t)(t + 2) * kstep; const char* b2 = last ? nB : cB + (size_t)(t + 2) * kstep;
;             const char* a3 = a2 + kstep; const char* b3 = b2 + kstep;
;             if (last && has_next) S.a_ready(nxt);
;             if constexpr (SP2) {
;             PG8_LDB(B0, 0, 0); PG8_LDB(B1, 0, 1); PG8_SCHED; PG8_LDA(At, 0, 0); PG8_STAGE(PG8_SA(1, 1), a1 + hstep, voffA);
;             PG8_WAIT_V(8); PG8_WAIT_L(0); PG8_BAR; PG8_MMA(0, 0, At, B0); PG8_MMA(0, 1, At, B1); PG8_BAR; PG8_SCHED;
;             PG8_LDA(At, 0, 1); PG8_STAGE(PG8_SB(0, 0), b2, voffB); PG8_STAGE(PG8_SB(0, 1), b2 + hstep, voffB); PG8_STAGE(PG8_SA(0, 0), a2, voffA);
;             PG8_WAIT_V(8); PG8_WAIT_L(0); PG8_BAR; PG8_MMA(1, 0, At, B0); PG8_MMA(1, 1, At, B1); PG8_BAR; PG8_SCHED;
.LBB0_134:
	ds_read_b128 v[144:147], v152
	ds_read_b128 v[156:159], v152 offset:1024
	ds_read_b128 v[160:163], v152 offset:2048
	ds_read_b128 v[164:167], v152 offset:3072
	ds_read_b128 v[168:171], v153
	ds_read_b128 v[172:175], v153 offset:1024
	ds_read_b128 v[182:185], v153 offset:2048
	ds_read_b128 v[186:189], v153 offset:3072
	s_add_u32 s20, s62, 0xfffc0080
	s_addc_u32 s21, s63, -1
	s_cmp_eq_u32 s92, 12
	s_cselect_b32 s73, s12, s21
	s_cselect_b32 s72, s13, s20
	s_cselect_b32 s67, s29, s91
	s_cselect_b32 s66, s31, s90
	v_lshl_add_u64 v[224:225], s[62:63], 0, v[136:137]
	s_add_i32 m0, s51, 0xc000
	ds_read_b128 v[190:193], v154
	ds_read_b128 v[194:197], v154 offset:1024
	ds_read_b128 v[198:201], v154 offset:2048
	ds_read_b128 v[202:205], v154 offset:3072
	ds_read_b128 v[206:209], v154 offset:4096
	ds_read_b128 v[212:215], v154 offset:5120
	ds_read_b128 v[216:219], v154 offset:6144
	ds_read_b128 v[220:223], v154 offset:7168
	global_load_lds_dwordx4 v[224:225], off
	v_lshl_add_u64 v[224:225], s[62:63], 0, v[138:139]
	s_add_i32 m0, s51, 0xe000
	s_nop 0
	global_load_lds_dwordx4 v[224:225], off
	s_waitcnt vmcnt(8)
	s_waitcnt lgkmcnt(0)
	s_barrier
	s_waitcnt lgkmcnt(0)
	v_mfma_f32_16x16x32_bf16 v[124:127], v[144:147], v[190:193], v[124:127]
	v_mfma_f32_16x16x32_bf16 v[120:123], v[160:163], v[190:193], v[120:123]
	v_mfma_f32_16x16x32_bf16 v[116:119], v[144:147], v[198:201], v[116:119]
	v_mfma_f32_16x16x32_bf16 v[108:111], v[160:163], v[198:201], v[108:111]
	v_mfma_f32_16x16x32_bf16 v[100:103], v[144:147], v[206:209], v[100:103]
	v_mfma_f32_16x16x32_bf16 v[92:95], v[160:163], v[206:209], v[92:95]
	v_mfma_f32_16x16x32_bf16 v[84:87], v[144:147], v[216:219], v[84:87]
	v_mfma_f32_16x16x32_bf16 v[76:79], v[160:163], v[216:219], v[76:79]
	v_mfma_f32_16x16x32_bf16 v[124:127], v[156:159], v[194:197], v[124:127]
	v_mfma_f32_16x16x32_bf16 v[120:123], v[164:167], v[194:197], v[120:123]
	v_mfma_f32_16x16x32_bf16 v[116:119], v[156:159], v[202:205], v[116:119]
	v_mfma_f32_16x16x32_bf16 v[108:111], v[164:167], v[202:205], v[108:111]
	v_mfma_f32_16x16x32_bf16 v[100:103], v[156:159], v[212:215], v[100:103]
	v_mfma_f32_16x16x32_bf16 v[92:95], v[164:167], v[212:215], v[92:95]
	v_mfma_f32_16x16x32_bf16 v[84:87], v[156:159], v[220:223], v[84:87]
	v_mfma_f32_16x16x32_bf16 v[76:79], v[164:167], v[220:223], v[76:79]
	v_mfma_f32_16x16x32_bf16 v[112:115], v[168:171], v[190:193], v[112:115]
	v_mfma_f32_16x16x32_bf16 v[104:107], v[182:185], v[190:193], v[104:107]
	v_mfma_f32_16x16x32_bf16 v[96:99], v[168:171], v[198:201], v[96:99]
	v_mfma_f32_16x16x32_bf16 v[88:91], v[182:185], v[198:201], v[88:91]
	v_mfma_f32_16x16x32_bf16 v[80:83], v[168:171], v[206:209], v[80:83]
	v_mfma_f32_16x16x32_bf16 v[72:75], v[182:185], v[206:209], v[72:75]
	v_mfma_f32_16x16x32_bf16 v[68:71], v[168:171], v[216:219], v[68:71]
	v_mfma_f32_16x16x32_bf16 v[64:67], v[182:185], v[216:219], v[64:67]
	v_mfma_f32_16x16x32_bf16 v[112:115], v[172:175], v[194:197], v[112:115]
	v_mfma_f32_16x16x32_bf16 v[104:107], v[186:189], v[194:197], v[104:107]
	v_mfma_f32_16x16x32_bf16 v[96:99], v[172:175], v[202:205], v[96:99]
	v_mfma_f32_16x16x32_bf16 v[88:91], v[186:189], v[202:205], v[88:91]
	v_mfma_f32_16x16x32_bf16 v[80:83], v[172:175], v[212:215], v[80:83]
	v_mfma_f32_16x16x32_bf16 v[72:75], v[186:189], v[212:215], v[72:75]
	v_mfma_f32_16x16x32_bf16 v[68:71], v[172:175], v[220:223], v[68:71]
	v_mfma_f32_16x16x32_bf16 v[64:67], v[186:189], v[220:223], v[64:67]
	s_barrier
	s_add_i32 s20, s81, s3
	v_lshl_add_u64 v[224:225], s[66:67], 0, v[132:133]
	s_mov_b32 m0, s20
	ds_read_b128 v[190:193], v154 offset:16384
	ds_read_b128 v[194:197], v154 offset:17408
	ds_read_b128 v[198:201], v154 offset:18432
	ds_read_b128 v[202:205], v154 offset:19456
	ds_read_b128 v[206:209], v154 offset:20480
	ds_read_b128 v[212:215], v154 offset:21504
	ds_read_b128 v[216:219], v154 offset:22528
	ds_read_b128 v[220:223], v154 offset:23552
	global_load_lds_dwordx4 v[224:225], off
	s_add_i32 m0, s20, 0x2000
	s_add_u32 s20, s66, 0x40000
	v_lshl_add_u64 v[226:227], s[66:67], 0, v[128:129]
	s_addc_u32 s21, s67, 0
	s_add_i32 s36, s82, s3
	global_load_lds_dwordx4 v[226:227], off
	v_lshl_add_u64 v[228:229], s[20:21], 0, v[132:133]
	s_mov_b32 m0, s36
	v_lshl_add_u64 v[230:231], s[72:73], 0, v[130:131]
	global_load_lds_dwordx4 v[228:229], off
	v_lshl_add_u64 v[228:229], s[20:21], 0, v[128:129]
	s_add_i32 m0, s36, 0x2000
	s_nop 0
	global_load_lds_dwordx4 v[228:229], off
	v_lshl_add_u64 v[228:229], s[72:73], 0, v[134:135]
	s_mov_b32 m0, s51
	s_nop 0
	global_load_lds_dwordx4 v[228:229], off
	s_mov_b32 m0, s75
	s_nop 0
	global_load_lds_dwordx4 v[230:231], off
	s_waitcnt vmcnt(8)
	s_waitcnt lgkmcnt(0)
	s_barrier
; #define PG8_STAGE(bufoff, gbase, voff) do { _Pragma("unroll") for (int _i = 0; _i < 2; ++_i) \
;         __builtin_amdgcn_global_load_lds((const unsigned*)((const char*)(gbase) + (voff)[_i]), (PG8_LAS unsigned*)(lds + (bufoff) + ldsw + _i * 8192), 16, 0, 0); } while (0)
; #define PG8_LDA(dst, b, h) do { _Pragma("unroll") for (int m = 0; m < 4; ++m) _Pragma("unroll") for (int k = 0; k < 2; ++k) dst[m][k] = *(const PG8_LAS bf16x8*)(lds + PG8_SA(b, h) + aoff + m * 2048 + k * 1024); } while (0)
; #define PG8_LDB(dst, b, h) do { _Pragma("unroll") for (int n = 0; n < 2; ++n) _Pragma("unroll") for (int k = 0; k < 2; ++k) dst[n][k] = *(const PG8_LAS bf16x8*)(lds + PG8_SB(b, h) + boff + n * 2048 + k * 1024); } while (0)
; #define PG8_MMA(ai, bj, At, Bt) do { __builtin_amdgcn_s_setprio(1); _Pragma("unroll") for (int m = 0; m < 4; ++m) _Pragma("unroll") for (int n = 0; n < 2; ++n) _Pragma("unroll") for (int k = 0; k < 2; ++k) \
;         acc[ai][bj][m][n] = __builtin_amdgcn_mfma_f32_16x16x32_bf16(Bt[n][k], At[m][k], acc[ai][bj][m][n], 0, 0, 0); __builtin_amdgcn_s_setprio(0); } while (0)
; #define PG8_WAIT_V(n) asm volatile("s_waitcnt vmcnt(" #n ")" ::: "memory")
; #define PG8_WAIT_L(n) asm volatile("s_waitcnt lgkmcnt(" #n ")" ::: "memory")
; #define PG8_BAR __builtin_amdgcn_s_barrier()
; #define PG8_SCHED __builtin_amdgcn_sched_barrier(0)
; template <class Epi, class Sched, bool ALIGN_EPI = false, bool SP2 = false>
; __device__ __forceinline__ void gemm_phase(PG8_LAS unsigned char* lds, const Gemm g, const Sched& S, const Epi& E) {
;     ...
;             PG8_WAIT_V(8); PG8_WAIT_L(0); PG8_BAR; PG8_MMA(1, 0, At, B0); PG8_MMA(1, 1, At, B1); PG8_BAR; PG8_SCHED;
;             PG8_LDB(B0, 1, 0); PG8_LDB(B1, 1, 1); PG8_SCHED; PG8_LDA(At, 1, 0); PG8_STAGE(PG8_SA(0, 1), a2 + hstep, voffA);
;             PG8_WAIT_V(8); PG8_WAIT_L(0); PG8_BAR; PG8_MMA(0, 0, At, B0); PG8_MMA(0, 1, At, B1); PG8_BAR; PG8_SCHED;
	s_waitcnt lgkmcnt(0)
	v_mfma_f32_16x16x32_bf16 v[60:63], v[144:147], v[190:193], v[60:63]
	v_mfma_f32_16x16x32_bf16 v[56:59], v[160:163], v[190:193], v[56:59]
	v_mfma_f32_16x16x32_bf16 v[52:55], v[144:147], v[198:201], v[52:55]
	v_mfma_f32_16x16x32_bf16 v[44:47], v[160:163], v[198:201], v[44:47]
	v_mfma_f32_16x16x32_bf16 v[36:39], v[144:147], v[206:209], v[36:39]
	v_mfma_f32_16x16x32_bf16 v[28:31], v[160:163], v[206:209], v[28:31]
	v_mfma_f32_16x16x32_bf16 v[20:23], v[144:147], v[216:219], v[20:23]
	v_mfma_f32_16x16x32_bf16 v[12:15], v[160:163], v[216:219], v[12:15]
	v_mfma_f32_16x16x32_bf16 v[60:63], v[156:159], v[194:197], v[60:63]
	v_mfma_f32_16x16x32_bf16 v[56:59], v[164:167], v[194:197], v[56:59]
	v_mfma_f32_16x16x32_bf16 v[52:55], v[156:159], v[202:205], v[52:55]
	v_mfma_f32_16x16x32_bf16 v[44:47], v[164:167], v[202:205], v[44:47]
	v_mfma_f32_16x16x32_bf16 v[36:39], v[156:159], v[212:215], v[36:39]
	v_mfma_f32_16x16x32_bf16 v[28:31], v[164:167], v[212:215], v[28:31]
	v_mfma_f32_16x16x32_bf16 v[20:23], v[156:159], v[220:223], v[20:23]
	v_mfma_f32_16x16x32_bf16 v[12:15], v[164:167], v[220:223], v[12:15]
	v_mfma_f32_16x16x32_bf16 v[48:51], v[168:171], v[190:193], v[48:51]
	v_mfma_f32_16x16x32_bf16 v[40:43], v[182:185], v[190:193], v[40:43]
	v_mfma_f32_16x16x32_bf16 v[32:35], v[168:171], v[198:201], v[32:35]
	v_mfma_f32_16x16x32_bf16 v[24:27], v[182:185], v[198:201], v[24:27]
	v_mfma_f32_16x16x32_bf16 v[16:19], v[168:171], v[206:209], v[16:19]
	v_mfma_f32_16x16x32_bf16 v[8:11], v[182:185], v[206:209], v[8:11]
	v_mfma_f32_16x16x32_bf16 v[4:7], v[168:171], v[216:219], v[4:7]
	v_mfma_f32_16x16x32_bf16 v[0:3], v[182:185], v[216:219], v[0:3]
	v_mfma_f32_16x16x32_bf16 v[48:51], v[172:175], v[194:197], v[48:51]
	v_mfma_f32_16x16x32_bf16 v[40:43], v[186:189], v[194:197], v[40:43]
	v_mfma_f32_16x16x32_bf16 v[32:35], v[172:175], v[202:205], v[32:35]
	v_mfma_f32_16x16x32_bf16 v[24:27], v[186:189], v[202:205], v[24:27]
	v_mfma_f32_16x16x32_bf16 v[16:19], v[172:175], v[212:215], v[16:19]
	v_mfma_f32_16x16x32_bf16 v[8:11], v[186:189], v[212:215], v[8:11]
	v_mfma_f32_16x16x32_bf16 v[4:7], v[172:175], v[220:223], v[4:7]
	v_mfma_f32_16x16x32_bf16 v[0:3], v[186:189], v[220:223], v[0:3]
	s_barrier
	s_add_i32 s36, 0, 0x18000
	v_add_u32_e32 v155, s36, v150
	s_add_i32 s37, 0, 0x1c000
	ds_read_b128 v[144:147], v155
	ds_read_b128 v[156:159], v155 offset:1024
	ds_read_b128 v[160:163], v155 offset:2048
	ds_read_b128 v[164:167], v155 offset:3072
	v_add_u32_e32 v155, s37, v150
	ds_read_b128 v[168:171], v155
	ds_read_b128 v[172:175], v155 offset:1024
	ds_read_b128 v[182:185], v155 offset:2048
	ds_read_b128 v[186:189], v155 offset:3072
	s_add_u32 s20, s72, 0x40000
	s_addc_u32 s21, s73, 0
	s_mov_b32 m0, s76
	v_lshl_add_u64 v[232:233], s[20:21], 0, v[134:135]
	ds_read_b128 v[190:193], v154 offset:32768
	ds_read_b128 v[194:197], v154 offset:33792
	ds_read_b128 v[198:201], v154 offset:34816
	ds_read_b128 v[202:205], v154 offset:35840
	ds_read_b128 v[206:209], v154 offset:36864
	ds_read_b128 v[212:215], v154 offset:37888
	ds_read_b128 v[216:219], v154 offset:38912
	ds_read_b128 v[220:223], v154 offset:39936
	global_load_lds_dwordx4 v[232:233], off
	v_lshl_add_u64 v[232:233], s[20:21], 0, v[130:131]
	s_mov_b32 m0, s77
	s_nop 0
	global_load_lds_dwordx4 v[232:233], off
	s_waitcnt vmcnt(8)
	s_waitcnt lgkmcnt(0)
	s_barrier
	s_waitcnt lgkmcnt(0)
	v_mfma_f32_16x16x32_bf16 v[124:127], v[144:147], v[190:193], v[124:127]
	v_mfma_f32_16x16x32_bf16 v[120:123], v[160:163], v[190:193], v[120:123]
	v_mfma_f32_16x16x32_bf16 v[116:119], v[144:147], v[198:201], v[116:119]
	v_mfma_f32_16x16x32_bf16 v[108:111], v[160:163], v[198:201], v[108:111]
	v_mfma_f32_16x16x32_bf16 v[100:103], v[144:147], v[206:209], v[100:103]
	v_mfma_f32_16x16x32_bf16 v[92:95], v[160:163], v[206:209], v[92:95]
	v_mfma_f32_16x16x32_bf16 v[84:87], v[144:147], v[216:219], v[84:87]
	v_mfma_f32_16x16x32_bf16 v[76:79], v[160:163], v[216:219], v[76:79]
	v_mfma_f32_16x16x32_bf16 v[124:127], v[156:159], v[194:197], v[124:127]
	v_mfma_f32_16x16x32_bf16 v[120:123], v[164:167], v[194:197], v[120:123]
	v_mfma_f32_16x16x32_bf16 v[116:119], v[156:159], v[202:205], v[116:119]
	v_mfma_f32_16x16x32_bf16 v[108:111], v[164:167], v[202:205], v[108:111]
	v_mfma_f32_16x16x32_bf16 v[100:103], v[156:159], v[212:215], v[100:103]
	v_mfma_f32_16x16x32_bf16 v[92:95], v[164:167], v[212:215], v[92:95]
	v_mfma_f32_16x16x32_bf16 v[84:87], v[156:159], v[220:223], v[84:87]
	v_mfma_f32_16x16x32_bf16 v[76:79], v[164:167], v[220:223], v[76:79]
	v_mfma_f32_16x16x32_bf16 v[112:115], v[168:171], v[190:193], v[112:115]
	v_mfma_f32_16x16x32_bf16 v[104:107], v[182:185], v[190:193], v[104:107]
	v_mfma_f32_16x16x32_bf16 v[96:99], v[168:171], v[198:201], v[96:99]
	v_mfma_f32_16x16x32_bf16 v[88:91], v[182:185], v[198:201], v[88:91]
	v_mfma_f32_16x16x32_bf16 v[80:83], v[168:171], v[206:209], v[80:83]
	v_mfma_f32_16x16x32_bf16 v[72:75], v[182:185], v[206:209], v[72:75]
	v_mfma_f32_16x16x32_bf16 v[68:71], v[168:171], v[216:219], v[68:71]
	v_mfma_f32_16x16x32_bf16 v[64:67], v[182:185], v[216:219], v[64:67]
	v_mfma_f32_16x16x32_bf16 v[112:115], v[172:175], v[194:197], v[112:115]
	v_mfma_f32_16x16x32_bf16 v[104:107], v[186:189], v[194:197], v[104:107]
	v_mfma_f32_16x16x32_bf16 v[96:99], v[172:175], v[202:205], v[96:99]
	v_mfma_f32_16x16x32_bf16 v[88:91], v[186:189], v[202:205], v[88:91]
	v_mfma_f32_16x16x32_bf16 v[80:83], v[172:175], v[212:215], v[80:83]
	v_mfma_f32_16x16x32_bf16 v[72:75], v[186:189], v[212:215], v[72:75]
	v_mfma_f32_16x16x32_bf16 v[68:71], v[172:175], v[220:223], v[68:71]
	v_mfma_f32_16x16x32_bf16 v[64:67], v[186:189], v[220:223], v[64:67]
	s_barrier
; #define PG8_STAGE(bufoff, gbase, voff) do { _Pragma("unroll") for (int _i = 0; _i < 2; ++_i) \
;         __builtin_amdgcn_global_load_lds((const unsigned*)((const char*)(gbase) + (voff)[_i]), (PG8_LAS unsigned*)(lds + (bufoff) + ldsw + _i * 8192), 16, 0, 0); } while (0)
; #define PG8_LDA(dst, b, h) do { _Pragma("unroll") for (int m = 0; m < 4; ++m) _Pragma("unroll") for (int k = 0; k < 2; ++k) dst[m][k] = *(const PG8_LAS bf16x8*)(lds + PG8_SA(b, h) + aoff + m * 2048 + k * 1024); } while (0)
; #define PG8_MMA(ai, bj, At, Bt) do { __builtin_amdgcn_s_setprio(1); _Pragma("unroll") for (int m = 0; m < 4; ++m) _Pragma("unroll") for (int n = 0; n < 2; ++n) _Pragma("unroll") for (int k = 0; k < 2; ++k) \
;         acc[ai][bj][m][n] = __builtin_amdgcn_mfma_f32_16x16x32_bf16(Bt[n][k], At[m][k], acc[ai][bj][m][n], 0, 0, 0); __builtin_amdgcn_s_setprio(0); } while (0)
; #define PG8_WAIT_V(n) asm volatile("s_waitcnt vmcnt(" #n ")" ::: "memory")
; #define PG8_WAIT_L(n) asm volatile("s_waitcnt lgkmcnt(" #n ")" ::: "memory")
; #define PG8_BAR __builtin_amdgcn_s_barrier()
; #define PG8_SCHED __builtin_amdgcn_sched_barrier(0)
; template <class Epi, class Sched, bool ALIGN_EPI = false, bool SP2 = false>
; __device__ __forceinline__ void gemm_phase(PG8_LAS unsigned char* lds, const Gemm g, const Sched& S, const Epi& E) {
;     ...
;             PG8_LDA(At, 1, 1); PG8_STAGE(PG8_SB(1, 0), b3, voffB); PG8_STAGE(PG8_SB(1, 1), b3 + hstep, voffB); PG8_STAGE(PG8_SA(1, 0), a3, voffA);
;             PG8_WAIT_V(8); PG8_WAIT_L(0); PG8_BAR; PG8_MMA(1, 0, At, B0); PG8_MMA(1, 1, At, B1); PG8_BAR; PG8_SCHED;
	s_add_i32 s20, s36, s3
	v_lshl_add_u64 v[224:225], v[224:225], 0, s[14:15]
	s_mov_b32 m0, s20
	ds_read_b128 v[190:193], v154 offset:49152
	ds_read_b128 v[194:197], v154 offset:50176
	ds_read_b128 v[198:201], v154 offset:51200
	ds_read_b128 v[202:205], v154 offset:52224
	ds_read_b128 v[206:209], v154 offset:53248
	ds_read_b128 v[212:215], v154 offset:54272
	ds_read_b128 v[216:219], v154 offset:55296
	ds_read_b128 v[220:223], v154 offset:56320
	global_load_lds_dwordx4 v[224:225], off
	s_add_i32 m0, s20, 0x2000
	s_add_u32 s20, s66, 0x40080
	v_lshl_add_u64 v[224:225], v[226:227], 0, s[14:15]
	s_addc_u32 s21, s67, 0
	s_add_i32 s36, s37, s3
	global_load_lds_dwordx4 v[224:225], off
	v_lshl_add_u64 v[224:225], s[20:21], 0, v[132:133]
	s_mov_b32 m0, s36
	s_nop 0
	global_load_lds_dwordx4 v[224:225], off
	v_lshl_add_u64 v[224:225], s[20:21], 0, v[128:129]
	s_add_i32 m0, s36, 0x2000
	s_nop 0
	global_load_lds_dwordx4 v[224:225], off
	v_lshl_add_u64 v[224:225], v[228:229], 0, s[14:15]
	s_mov_b32 m0, s10
	s_nop 0
	global_load_lds_dwordx4 v[224:225], off
	v_lshl_add_u64 v[224:225], v[230:231], 0, s[14:15]
	s_mov_b32 m0, s11
	s_nop 0
	global_load_lds_dwordx4 v[224:225], off
	s_waitcnt vmcnt(8)
	s_waitcnt lgkmcnt(0)
	s_barrier
	s_waitcnt lgkmcnt(0)
	v_mfma_f32_16x16x32_bf16 v[60:63], v[144:147], v[190:193], v[60:63]
	v_mfma_f32_16x16x32_bf16 v[56:59], v[160:163], v[190:193], v[56:59]
	v_mfma_f32_16x16x32_bf16 v[52:55], v[144:147], v[198:201], v[52:55]
	v_mfma_f32_16x16x32_bf16 v[44:47], v[160:163], v[198:201], v[44:47]
	v_mfma_f32_16x16x32_bf16 v[36:39], v[144:147], v[206:209], v[36:39]
	v_mfma_f32_16x16x32_bf16 v[28:31], v[160:163], v[206:209], v[28:31]
	v_mfma_f32_16x16x32_bf16 v[20:23], v[144:147], v[216:219], v[20:23]
	v_mfma_f32_16x16x32_bf16 v[12:15], v[160:163], v[216:219], v[12:15]
	v_mfma_f32_16x16x32_bf16 v[60:63], v[156:159], v[194:197], v[60:63]
	v_mfma_f32_16x16x32_bf16 v[56:59], v[164:167], v[194:197], v[56:59]
	v_mfma_f32_16x16x32_bf16 v[52:55], v[156:159], v[202:205], v[52:55]
	v_mfma_f32_16x16x32_bf16 v[44:47], v[164:167], v[202:205], v[44:47]
	v_mfma_f32_16x16x32_bf16 v[36:39], v[156:159], v[212:215], v[36:39]
	v_mfma_f32_16x16x32_bf16 v[28:31], v[164:167], v[212:215], v[28:31]
	v_mfma_f32_16x16x32_bf16 v[20:23], v[156:159], v[220:223], v[20:23]
	v_mfma_f32_16x16x32_bf16 v[12:15], v[164:167], v[220:223], v[12:15]
	v_mfma_f32_16x16x32_bf16 v[48:51], v[168:171], v[190:193], v[48:51]
	v_mfma_f32_16x16x32_bf16 v[40:43], v[182:185], v[190:193], v[40:43]
	v_mfma_f32_16x16x32_bf16 v[32:35], v[168:171], v[198:201], v[32:35]
	v_mfma_f32_16x16x32_bf16 v[24:27], v[182:185], v[198:201], v[24:27]
	v_mfma_f32_16x16x32_bf16 v[16:19], v[168:171], v[206:209], v[16:19]
	v_mfma_f32_16x16x32_bf16 v[8:11], v[182:185], v[206:209], v[8:11]
	v_mfma_f32_16x16x32_bf16 v[4:7], v[168:171], v[216:219], v[4:7]
	v_mfma_f32_16x16x32_bf16 v[0:3], v[182:185], v[216:219], v[0:3]
	v_mfma_f32_16x16x32_bf16 v[48:51], v[172:175], v[194:197], v[48:51]
	v_mfma_f32_16x16x32_bf16 v[40:43], v[186:189], v[194:197], v[40:43]
	v_mfma_f32_16x16x32_bf16 v[32:35], v[172:175], v[202:205], v[32:35]
	v_mfma_f32_16x16x32_bf16 v[24:27], v[186:189], v[202:205], v[24:27]
	v_mfma_f32_16x16x32_bf16 v[16:19], v[172:175], v[212:215], v[16:19]
	v_mfma_f32_16x16x32_bf16 v[8:11], v[186:189], v[212:215], v[8:11]
	v_mfma_f32_16x16x32_bf16 v[4:7], v[172:175], v[220:223], v[4:7]
	v_mfma_f32_16x16x32_bf16 v[0:3], v[186:189], v[220:223], v[0:3]
	s_barrier
	s_add_i32 s92, s92, 2
	s_add_u32 s62, s62, 0x100
	s_addc_u32 s63, s63, 0
	s_add_u32 s90, s90, 0x100
	s_addc_u32 s91, s91, 0
	s_cmp_gt_u32 s92, 13
	s_cbranch_scc0 .LBB0_134
	s_and_b64 vcc, exec, s[26:27]
	s_cbranch_vccz .LBB0_137
	s_barrier

; #define PG8_STAGE(bufoff, gbase, voff) do { _Pragma("unroll") for (int _i = 0; _i < 2; ++_i) \
;         __builtin_amdgcn_global_load_lds((const unsigned*)((const char*)(gbase) + (voff)[_i]), (PG8_LAS unsigned*)(lds + (bufoff) + ldsw + _i * 8192), 16, 0, 0); } while (0)
; #define PG8_LDA(dst, b, h) do { _Pragma("unroll") for (int m = 0; m < 4; ++m) _Pragma("unroll") for (int k = 0; k < 2; ++k) dst[m][k] = *(const PG8_LAS bf16x8*)(lds + PG8_SA(b, h) + aoff + m * 2048 + k * 1024); } while (0)
; #define PG8_LDB(dst, b, h) do { _Pragma("unroll") for (int n = 0; n < 2; ++n) _Pragma("unroll") for (int k = 0; k < 2; ++k) dst[n][k] = *(const PG8_LAS bf16x8*)(lds + PG8_SB(b, h) + boff + n * 2048 + k * 1024); } while (0)
; #define PG8_MMA(ai, bj, At, Bt) do { __builtin_amdgcn_s_setprio(1); _Pragma("unroll") for (int m = 0; m < 4; ++m) _Pragma("unroll") for (int n = 0; n < 2; ++n) _Pragma("unroll") for (int k = 0; k < 2; ++k) \
;         acc[ai][bj][m][n] = __builtin_amdgcn_mfma_f32_16x16x32_bf16(Bt[n][k], At[m][k], acc[ai][bj][m][n], 0, 0, 0); __builtin_amdgcn_s_setprio(0); } while (0)
; #define PG8_WAIT_V(n) asm volatile("s_waitcnt vmcnt(" #n ")" ::: "memory")
; #define PG8_BAR __builtin_amdgcn_s_barrier()
; template <class Epi, class Sched, bool ALIGN_EPI = false, bool SP2 = false>
; __device__ __forceinline__ void gemm_phase(PG8_LAS unsigned char* lds, const Gemm g, const Sched& S, const Epi& E) {
;     ...
;         for (int t = 0; t < nt_u; t += 2) {
;             const bool last = (t == nt_u - 2);
;             const char* a1 = cA + (size_t)(t + 1) * kstep;
;             const char* a2 = last ? nA : cA + (size_t)(t + 2) * kstep; const char* b2 = last ? nB : cB + (size_t)(t + 2) * kstep;
;             const char* a3 = a2 + kstep; const char* b3 = b2 + kstep;
;             if (last && has_next) S.a_ready(nxt);
;             if constexpr (SP2) {
;             PG8_LDB(B0, 0, 0); PG8_LDB(B1, 0, 1); PG8_SCHED; PG8_LDA(At, 0, 0); PG8_STAGE(PG8_SA(1, 1), a1 + hstep, voffA);
;             PG8_WAIT_V(8); PG8_WAIT_L(0); PG8_BAR; PG8_MMA(0, 0, At, B0); PG8_MMA(0, 1, At, B1); PG8_BAR; PG8_SCHED;
;             PG8_LDA(At, 0, 1); PG8_STAGE(PG8_SB(0, 0), b2, voffB); PG8_STAGE(PG8_SB(0, 1), b2 + hstep, voffB); PG8_STAGE(PG8_SA(0, 0), a2, voffA);
;             PG8_WAIT_V(8); PG8_WAIT_L(0); PG8_BAR; PG8_MMA(1, 0, At, B0); PG8_MMA(1, 1, At, B1); PG8_BAR; PG8_SCHED;
.LBB0_312:
	ds_read_b128 v[144:147], v151
	ds_read_b128 v[154:157], v151 offset:1024
	ds_read_b128 v[158:161], v151 offset:2048
	ds_read_b128 v[162:165], v151 offset:3072
	ds_read_b128 v[166:169], v152
	ds_read_b128 v[170:173], v152 offset:1024
	ds_read_b128 v[184:187], v152 offset:2048
	ds_read_b128 v[188:191], v152 offset:3072
	s_add_u32 s44, s42, 0x100
	s_addc_u32 s45, s43, 0
	s_cmp_eq_u32 s83, 2
	s_cselect_b32 s51, s1, s45
	s_cselect_b32 s50, s0, s44
	s_cselect_b32 s47, s41, s13
	s_cselect_b32 s46, s40, s12
	v_lshl_add_u64 v[174:175], s[42:43], 0, v[136:137]
	s_add_i32 m0, s63, 0xc000
	ds_read_b128 v[192:195], v153
	ds_read_b128 v[196:199], v153 offset:1024
	ds_read_b128 v[200:203], v153 offset:2048
	ds_read_b128 v[204:207], v153 offset:3072
	ds_read_b128 v[212:215], v153 offset:4096
	ds_read_b128 v[216:219], v153 offset:5120
	ds_read_b128 v[220:223], v153 offset:6144
	ds_read_b128 v[224:227], v153 offset:7168
	global_load_lds_dwordx4 v[174:175], off
	v_lshl_add_u64 v[174:175], s[42:43], 0, v[138:139]
	s_add_i32 m0, s63, 0xe000
	s_nop 0
	global_load_lds_dwordx4 v[174:175], off
	s_waitcnt vmcnt(8)
	s_waitcnt lgkmcnt(0)
	s_barrier
	s_waitcnt lgkmcnt(0)
	v_mfma_f32_16x16x32_bf16 v[124:127], v[144:147], v[192:195], v[124:127]
	v_mfma_f32_16x16x32_bf16 v[120:123], v[158:161], v[192:195], v[120:123]
	v_mfma_f32_16x16x32_bf16 v[116:119], v[144:147], v[200:203], v[116:119]
	v_mfma_f32_16x16x32_bf16 v[108:111], v[158:161], v[200:203], v[108:111]
	v_mfma_f32_16x16x32_bf16 v[100:103], v[144:147], v[212:215], v[100:103]
	v_mfma_f32_16x16x32_bf16 v[92:95], v[158:161], v[212:215], v[92:95]
	v_mfma_f32_16x16x32_bf16 v[84:87], v[144:147], v[220:223], v[84:87]
	v_mfma_f32_16x16x32_bf16 v[76:79], v[158:161], v[220:223], v[76:79]
	v_mfma_f32_16x16x32_bf16 v[124:127], v[154:157], v[196:199], v[124:127]
	v_mfma_f32_16x16x32_bf16 v[120:123], v[162:165], v[196:199], v[120:123]
	v_mfma_f32_16x16x32_bf16 v[116:119], v[154:157], v[204:207], v[116:119]
	v_mfma_f32_16x16x32_bf16 v[108:111], v[162:165], v[204:207], v[108:111]
	v_mfma_f32_16x16x32_bf16 v[100:103], v[154:157], v[216:219], v[100:103]
	v_mfma_f32_16x16x32_bf16 v[92:95], v[162:165], v[216:219], v[92:95]
	v_mfma_f32_16x16x32_bf16 v[84:87], v[154:157], v[224:227], v[84:87]
	v_mfma_f32_16x16x32_bf16 v[76:79], v[162:165], v[224:227], v[76:79]
	v_mfma_f32_16x16x32_bf16 v[112:115], v[166:169], v[192:195], v[112:115]
	v_mfma_f32_16x16x32_bf16 v[104:107], v[184:187], v[192:195], v[104:107]
	v_mfma_f32_16x16x32_bf16 v[96:99], v[166:169], v[200:203], v[96:99]
	v_mfma_f32_16x16x32_bf16 v[88:91], v[184:187], v[200:203], v[88:91]
	v_mfma_f32_16x16x32_bf16 v[80:83], v[166:169], v[212:215], v[80:83]
	v_mfma_f32_16x16x32_bf16 v[72:75], v[184:187], v[212:215], v[72:75]
	v_mfma_f32_16x16x32_bf16 v[68:71], v[166:169], v[220:223], v[68:71]
	v_mfma_f32_16x16x32_bf16 v[64:67], v[184:187], v[220:223], v[64:67]
	v_mfma_f32_16x16x32_bf16 v[112:115], v[170:173], v[196:199], v[112:115]
	v_mfma_f32_16x16x32_bf16 v[104:107], v[188:191], v[196:199], v[104:107]
	v_mfma_f32_16x16x32_bf16 v[96:99], v[170:173], v[204:207], v[96:99]
	v_mfma_f32_16x16x32_bf16 v[88:91], v[188:191], v[204:207], v[88:91]
	v_mfma_f32_16x16x32_bf16 v[80:83], v[170:173], v[216:219], v[80:83]
	v_mfma_f32_16x16x32_bf16 v[72:75], v[188:191], v[216:219], v[72:75]
	v_mfma_f32_16x16x32_bf16 v[68:71], v[170:173], v[224:227], v[68:71]
	v_mfma_f32_16x16x32_bf16 v[64:67], v[188:191], v[224:227], v[64:67]
	s_barrier
	s_add_i32 s20, s76, s3
	v_lshl_add_u64 v[174:175], s[46:47], 0, v[132:133]
	s_mov_b32 m0, s20
	ds_read_b128 v[192:195], v153 offset:16384
	ds_read_b128 v[196:199], v153 offset:17408
	ds_read_b128 v[200:203], v153 offset:18432
	ds_read_b128 v[204:207], v153 offset:19456
	ds_read_b128 v[212:215], v153 offset:20480
	ds_read_b128 v[216:219], v153 offset:21504
	ds_read_b128 v[220:223], v153 offset:22528
	ds_read_b128 v[224:227], v153 offset:23552
	global_load_lds_dwordx4 v[174:175], off
	s_add_i32 m0, s20, 0x2000
	s_add_u32 s20, s46, 0x18000
	v_lshl_add_u64 v[208:209], s[46:47], 0, v[128:129]
	s_addc_u32 s21, s47, 0
	s_add_i32 s42, s77, s3
	global_load_lds_dwordx4 v[208:209], off
	v_lshl_add_u64 v[228:229], s[20:21], 0, v[132:133]
	s_mov_b32 m0, s42
	v_lshl_add_u64 v[230:231], s[50:51], 0, v[130:131]
	global_load_lds_dwordx4 v[228:229], off
	v_lshl_add_u64 v[228:229], s[20:21], 0, v[128:129]
	s_add_i32 m0, s42, 0x2000
	s_nop 0
	global_load_lds_dwordx4 v[228:229], off
	v_lshl_add_u64 v[228:229], s[50:51], 0, v[134:135]
	s_mov_b32 m0, s63
	s_nop 0
	global_load_lds_dwordx4 v[228:229], off
	s_mov_b32 m0, s66
	s_nop 0
	global_load_lds_dwordx4 v[230:231], off
	s_waitcnt vmcnt(8)
	s_waitcnt lgkmcnt(0)
	s_barrier
; #define PG8_STAGE(bufoff, gbase, voff) do { _Pragma("unroll") for (int _i = 0; _i < 2; ++_i) \
;         __builtin_amdgcn_global_load_lds((const unsigned*)((const char*)(gbase) + (voff)[_i]), (PG8_LAS unsigned*)(lds + (bufoff) + ldsw + _i * 8192), 16, 0, 0); } while (0)
; #define PG8_LDA(dst, b, h) do { _Pragma("unroll") for (int m = 0; m < 4; ++m) _Pragma("unroll") for (int k = 0; k < 2; ++k) dst[m][k] = *(const PG8_LAS bf16x8*)(lds + PG8_SA(b, h) + aoff + m * 2048 + k * 1024); } while (0)
; #define PG8_LDB(dst, b, h) do { _Pragma("unroll") for (int n = 0; n < 2; ++n) _Pragma("unroll") for (int k = 0; k < 2; ++k) dst[n][k] = *(const PG8_LAS bf16x8*)(lds + PG8_SB(b, h) + boff + n * 2048 + k * 1024); } while (0)
; #define PG8_MMA(ai, bj, At, Bt) do { __builtin_amdgcn_s_setprio(1); _Pragma("unroll") for (int m = 0; m < 4; ++m) _Pragma("unroll") for (int n = 0; n < 2; ++n) _Pragma("unroll") for (int k = 0; k < 2; ++k) \
;         acc[ai][bj][m][n] = __builtin_amdgcn_mfma_f32_16x16x32_bf16(Bt[n][k], At[m][k], acc[ai][bj][m][n], 0, 0, 0); __builtin_amdgcn_s_setprio(0); } while (0)
; #define PG8_WAIT_V(n) asm volatile("s_waitcnt vmcnt(" #n ")" ::: "memory")
; #define PG8_WAIT_L(n) asm volatile("s_waitcnt lgkmcnt(" #n ")" ::: "memory")
; #define PG8_BAR __builtin_amdgcn_s_barrier()
; #define PG8_SCHED __builtin_amdgcn_sched_barrier(0)
; template <class Epi, class Sched, bool ALIGN_EPI = false, bool SP2 = false>
; __device__ __forceinline__ void gemm_phase(PG8_LAS unsigned char* lds, const Gemm g, const Sched& S, const Epi& E) {
;     ...
;             PG8_WAIT_V(8); PG8_WAIT_L(0); PG8_BAR; PG8_MMA(1, 0, At, B0); PG8_MMA(1, 1, At, B1); PG8_BAR; PG8_SCHED;
;             PG8_LDB(B0, 1, 0); PG8_LDB(B1, 1, 1); PG8_SCHED; PG8_LDA(At, 1, 0); PG8_STAGE(PG8_SA(0, 1), a2 + hstep, voffA);
;             PG8_WAIT_V(8); PG8_WAIT_L(0); PG8_BAR; PG8_MMA(0, 0, At, B0); PG8_MMA(0, 1, At, B1); PG8_BAR; PG8_SCHED;
	s_waitcnt lgkmcnt(0)
	v_mfma_f32_16x16x32_bf16 v[60:63], v[144:147], v[192:195], v[60:63]
	v_mfma_f32_16x16x32_bf16 v[56:59], v[158:161], v[192:195], v[56:59]
	v_mfma_f32_16x16x32_bf16 v[52:55], v[144:147], v[200:203], v[52:55]
	v_mfma_f32_16x16x32_bf16 v[44:47], v[158:161], v[200:203], v[44:47]
	v_mfma_f32_16x16x32_bf16 v[36:39], v[144:147], v[212:215], v[36:39]
	v_mfma_f32_16x16x32_bf16 v[28:31], v[158:161], v[212:215], v[28:31]
	v_mfma_f32_16x16x32_bf16 v[20:23], v[144:147], v[220:223], v[20:23]
	v_mfma_f32_16x16x32_bf16 v[12:15], v[158:161], v[220:223], v[12:15]
	v_mfma_f32_16x16x32_bf16 v[60:63], v[154:157], v[196:199], v[60:63]
	v_mfma_f32_16x16x32_bf16 v[56:59], v[162:165], v[196:199], v[56:59]
	v_mfma_f32_16x16x32_bf16 v[52:55], v[154:157], v[204:207], v[52:55]
	v_mfma_f32_16x16x32_bf16 v[44:47], v[162:165], v[204:207], v[44:47]
	v_mfma_f32_16x16x32_bf16 v[36:39], v[154:157], v[216:219], v[36:39]
	v_mfma_f32_16x16x32_bf16 v[28:31], v[162:165], v[216:219], v[28:31]
	v_mfma_f32_16x16x32_bf16 v[20:23], v[154:157], v[224:227], v[20:23]
	v_mfma_f32_16x16x32_bf16 v[12:15], v[162:165], v[224:227], v[12:15]
	v_mfma_f32_16x16x32_bf16 v[48:51], v[166:169], v[192:195], v[48:51]
	v_mfma_f32_16x16x32_bf16 v[40:43], v[184:187], v[192:195], v[40:43]
	v_mfma_f32_16x16x32_bf16 v[32:35], v[166:169], v[200:203], v[32:35]
	v_mfma_f32_16x16x32_bf16 v[24:27], v[184:187], v[200:203], v[24:27]
	v_mfma_f32_16x16x32_bf16 v[16:19], v[166:169], v[212:215], v[16:19]
	v_mfma_f32_16x16x32_bf16 v[8:11], v[184:187], v[212:215], v[8:11]
	v_mfma_f32_16x16x32_bf16 v[4:7], v[166:169], v[220:223], v[4:7]
	v_mfma_f32_16x16x32_bf16 v[0:3], v[184:187], v[220:223], v[0:3]
	v_mfma_f32_16x16x32_bf16 v[48:51], v[170:173], v[196:199], v[48:51]
	v_mfma_f32_16x16x32_bf16 v[40:43], v[188:191], v[196:199], v[40:43]
	v_mfma_f32_16x16x32_bf16 v[32:35], v[170:173], v[204:207], v[32:35]
	v_mfma_f32_16x16x32_bf16 v[24:27], v[188:191], v[204:207], v[24:27]
	v_mfma_f32_16x16x32_bf16 v[16:19], v[170:173], v[216:219], v[16:19]
	v_mfma_f32_16x16x32_bf16 v[8:11], v[188:191], v[216:219], v[8:11]
	v_mfma_f32_16x16x32_bf16 v[4:7], v[170:173], v[224:227], v[4:7]
	v_mfma_f32_16x16x32_bf16 v[0:3], v[188:191], v[224:227], v[0:3]
	s_barrier
	s_add_i32 s42, 0, 0x18000
	s_add_i32 s43, 0, 0x1c000
	v_add_u32_e32 v162, s42, v149
	v_add_u32_e32 v177, s43, v149
	ds_read_b128 v[144:147], v162
	ds_read_b128 v[154:157], v162 offset:1024
	ds_read_b128 v[158:161], v162 offset:2048
	ds_read_b128 v[162:165], v162 offset:3072
	ds_read_b128 v[166:169], v177
	ds_read_b128 v[170:173], v177 offset:1024
	ds_read_b128 v[184:187], v177 offset:2048
	ds_read_b128 v[188:191], v177 offset:3072
	s_add_u32 s20, s50, 0x18000
	s_addc_u32 s21, s51, 0
	s_mov_b32 m0, s67
	v_lshl_add_u64 v[232:233], s[20:21], 0, v[134:135]
	ds_read_b128 v[192:195], v153 offset:32768
	ds_read_b128 v[196:199], v153 offset:33792
	ds_read_b128 v[200:203], v153 offset:34816
	ds_read_b128 v[204:207], v153 offset:35840
	ds_read_b128 v[212:215], v153 offset:36864
	ds_read_b128 v[216:219], v153 offset:37888
	ds_read_b128 v[220:223], v153 offset:38912
	ds_read_b128 v[224:227], v153 offset:39936
	global_load_lds_dwordx4 v[232:233], off
	v_lshl_add_u64 v[232:233], s[20:21], 0, v[130:131]
	s_mov_b32 m0, s72
	s_nop 0
	global_load_lds_dwordx4 v[232:233], off
	s_waitcnt vmcnt(8)
	s_waitcnt lgkmcnt(0)
	s_barrier
	s_waitcnt lgkmcnt(0)
	v_mfma_f32_16x16x32_bf16 v[124:127], v[144:147], v[192:195], v[124:127]
	v_mfma_f32_16x16x32_bf16 v[120:123], v[158:161], v[192:195], v[120:123]
	v_mfma_f32_16x16x32_bf16 v[116:119], v[144:147], v[200:203], v[116:119]
	v_mfma_f32_16x16x32_bf16 v[108:111], v[158:161], v[200:203], v[108:111]
	v_mfma_f32_16x16x32_bf16 v[100:103], v[144:147], v[212:215], v[100:103]
	v_mfma_f32_16x16x32_bf16 v[92:95], v[158:161], v[212:215], v[92:95]
	v_mfma_f32_16x16x32_bf16 v[84:87], v[144:147], v[220:223], v[84:87]
	v_mfma_f32_16x16x32_bf16 v[76:79], v[158:161], v[220:223], v[76:79]
	v_mfma_f32_16x16x32_bf16 v[124:127], v[154:157], v[196:199], v[124:127]
	v_mfma_f32_16x16x32_bf16 v[120:123], v[162:165], v[196:199], v[120:123]
	v_mfma_f32_16x16x32_bf16 v[116:119], v[154:157], v[204:207], v[116:119]
	v_mfma_f32_16x16x32_bf16 v[108:111], v[162:165], v[204:207], v[108:111]
	v_mfma_f32_16x16x32_bf16 v[100:103], v[154:157], v[216:219], v[100:103]
	v_mfma_f32_16x16x32_bf16 v[92:95], v[162:165], v[216:219], v[92:95]
	v_mfma_f32_16x16x32_bf16 v[84:87], v[154:157], v[224:227], v[84:87]
	v_mfma_f32_16x16x32_bf16 v[76:79], v[162:165], v[224:227], v[76:79]
	v_mfma_f32_16x16x32_bf16 v[112:115], v[166:169], v[192:195], v[112:115]
	v_mfma_f32_16x16x32_bf16 v[104:107], v[184:187], v[192:195], v[104:107]
	v_mfma_f32_16x16x32_bf16 v[96:99], v[166:169], v[200:203], v[96:99]
	v_mfma_f32_16x16x32_bf16 v[88:91], v[184:187], v[200:203], v[88:91]
	v_mfma_f32_16x16x32_bf16 v[80:83], v[166:169], v[212:215], v[80:83]
	v_mfma_f32_16x16x32_bf16 v[72:75], v[184:187], v[212:215], v[72:75]
	v_mfma_f32_16x16x32_bf16 v[68:71], v[166:169], v[220:223], v[68:71]
	v_mfma_f32_16x16x32_bf16 v[64:67], v[184:187], v[220:223], v[64:67]
	v_mfma_f32_16x16x32_bf16 v[112:115], v[170:173], v[196:199], v[112:115]
	v_mfma_f32_16x16x32_bf16 v[104:107], v[188:191], v[196:199], v[104:107]
	v_mfma_f32_16x16x32_bf16 v[96:99], v[170:173], v[204:207], v[96:99]
	v_mfma_f32_16x16x32_bf16 v[88:91], v[188:191], v[204:207], v[88:91]
	v_mfma_f32_16x16x32_bf16 v[80:83], v[170:173], v[216:219], v[80:83]
	v_mfma_f32_16x16x32_bf16 v[72:75], v[188:191], v[216:219], v[72:75]
	v_mfma_f32_16x16x32_bf16 v[68:71], v[170:173], v[224:227], v[68:71]
	v_mfma_f32_16x16x32_bf16 v[64:67], v[188:191], v[224:227], v[64:67]
	s_barrier
; #define PG8_STAGE(bufoff, gbase, voff) do { _Pragma("unroll") for (int _i = 0; _i < 2; ++_i) \
;         __builtin_amdgcn_global_load_lds((const unsigned*)((const char*)(gbase) + (voff)[_i]), (PG8_LAS unsigned*)(lds + (bufoff) + ldsw + _i * 8192), 16, 0, 0); } while (0)
; #define PG8_LDA(dst, b, h) do { _Pragma("unroll") for (int m = 0; m < 4; ++m) _Pragma("unroll") for (int k = 0; k < 2; ++k) dst[m][k] = *(const PG8_LAS bf16x8*)(lds + PG8_SA(b, h) + aoff + m * 2048 + k * 1024); } while (0)
; #define PG8_MMA(ai, bj, At, Bt) do { __builtin_amdgcn_s_setprio(1); _Pragma("unroll") for (int m = 0; m < 4; ++m) _Pragma("unroll") for (int n = 0; n < 2; ++n) _Pragma("unroll") for (int k = 0; k < 2; ++k) \
;         acc[ai][bj][m][n] = __builtin_amdgcn_mfma_f32_16x16x32_bf16(Bt[n][k], At[m][k], acc[ai][bj][m][n], 0, 0, 0); __builtin_amdgcn_s_setprio(0); } while (0)
; #define PG8_WAIT_V(n) asm volatile("s_waitcnt vmcnt(" #n ")" ::: "memory")
; #define PG8_WAIT_L(n) asm volatile("s_waitcnt lgkmcnt(" #n ")" ::: "memory")
; #define PG8_BAR __builtin_amdgcn_s_barrier()
; #define PG8_SCHED __builtin_amdgcn_sched_barrier(0)
; template <class Epi, class Sched, bool ALIGN_EPI = false, bool SP2 = false>
; __device__ __forceinline__ void gemm_phase(PG8_LAS unsigned char* lds, const Gemm g, const Sched& S, const Epi& E) {
;     ...
;             PG8_LDA(At, 1, 1); PG8_STAGE(PG8_SB(1, 0), b3, voffB); PG8_STAGE(PG8_SB(1, 1), b3 + hstep, voffB); PG8_STAGE(PG8_SA(1, 0), a3, voffA);
;             PG8_WAIT_V(8); PG8_WAIT_L(0); PG8_BAR; PG8_MMA(1, 0, At, B0); PG8_MMA(1, 1, At, B1); PG8_BAR; PG8_SCHED;
	s_add_i32 s20, s42, s3
	v_lshl_add_u64 v[174:175], v[174:175], 0, s[36:37]
	s_mov_b32 m0, s20
	ds_read_b128 v[192:195], v153 offset:49152
	ds_read_b128 v[196:199], v153 offset:50176
	ds_read_b128 v[200:203], v153 offset:51200
	ds_read_b128 v[204:207], v153 offset:52224
	ds_read_b128 v[212:215], v153 offset:53248
	ds_read_b128 v[216:219], v153 offset:54272
	ds_read_b128 v[220:223], v153 offset:55296
	ds_read_b128 v[224:227], v153 offset:56320
	global_load_lds_dwordx4 v[174:175], off
	s_add_i32 m0, s20, 0x2000
	s_add_u32 s20, s46, 0x18080
	v_lshl_add_u64 v[174:175], v[208:209], 0, s[36:37]
	s_addc_u32 s21, s47, 0
	s_add_i32 s42, s43, s3
	global_load_lds_dwordx4 v[174:175], off
	v_lshl_add_u64 v[174:175], s[20:21], 0, v[132:133]
	s_mov_b32 m0, s42
	s_nop 0
	global_load_lds_dwordx4 v[174:175], off
	v_lshl_add_u64 v[174:175], s[20:21], 0, v[128:129]
	s_add_i32 m0, s42, 0x2000
	s_nop 0
	global_load_lds_dwordx4 v[174:175], off
	v_lshl_add_u64 v[174:175], v[228:229], 0, s[36:37]
	s_mov_b32 m0, s10
	s_nop 0
	global_load_lds_dwordx4 v[174:175], off
	v_lshl_add_u64 v[174:175], v[230:231], 0, s[36:37]
	s_mov_b32 m0, s11
	s_nop 0
	global_load_lds_dwordx4 v[174:175], off
	s_waitcnt vmcnt(8)
	s_waitcnt lgkmcnt(0)
	s_barrier
	s_waitcnt lgkmcnt(0)
	v_mfma_f32_16x16x32_bf16 v[60:63], v[144:147], v[192:195], v[60:63]
	v_mfma_f32_16x16x32_bf16 v[56:59], v[158:161], v[192:195], v[56:59]
	v_mfma_f32_16x16x32_bf16 v[52:55], v[144:147], v[200:203], v[52:55]
	v_mfma_f32_16x16x32_bf16 v[44:47], v[158:161], v[200:203], v[44:47]
	v_mfma_f32_16x16x32_bf16 v[36:39], v[144:147], v[212:215], v[36:39]
	v_mfma_f32_16x16x32_bf16 v[28:31], v[158:161], v[212:215], v[28:31]
	v_mfma_f32_16x16x32_bf16 v[20:23], v[144:147], v[220:223], v[20:23]
	v_mfma_f32_16x16x32_bf16 v[12:15], v[158:161], v[220:223], v[12:15]
	v_mfma_f32_16x16x32_bf16 v[60:63], v[154:157], v[196:199], v[60:63]
	v_mfma_f32_16x16x32_bf16 v[56:59], v[162:165], v[196:199], v[56:59]
	v_mfma_f32_16x16x32_bf16 v[52:55], v[154:157], v[204:207], v[52:55]
	v_mfma_f32_16x16x32_bf16 v[44:47], v[162:165], v[204:207], v[44:47]
	v_mfma_f32_16x16x32_bf16 v[36:39], v[154:157], v[216:219], v[36:39]
	v_mfma_f32_16x16x32_bf16 v[28:31], v[162:165], v[216:219], v[28:31]
	v_mfma_f32_16x16x32_bf16 v[20:23], v[154:157], v[224:227], v[20:23]
	v_mfma_f32_16x16x32_bf16 v[12:15], v[162:165], v[224:227], v[12:15]
	v_mfma_f32_16x16x32_bf16 v[48:51], v[166:169], v[192:195], v[48:51]
	v_mfma_f32_16x16x32_bf16 v[40:43], v[184:187], v[192:195], v[40:43]
	v_mfma_f32_16x16x32_bf16 v[32:35], v[166:169], v[200:203], v[32:35]
	v_mfma_f32_16x16x32_bf16 v[24:27], v[184:187], v[200:203], v[24:27]
	v_mfma_f32_16x16x32_bf16 v[16:19], v[166:169], v[212:215], v[16:19]
	v_mfma_f32_16x16x32_bf16 v[8:11], v[184:187], v[212:215], v[8:11]
	v_mfma_f32_16x16x32_bf16 v[4:7], v[166:169], v[220:223], v[4:7]
	v_mfma_f32_16x16x32_bf16 v[0:3], v[184:187], v[220:223], v[0:3]
	v_mfma_f32_16x16x32_bf16 v[48:51], v[170:173], v[196:199], v[48:51]
	v_mfma_f32_16x16x32_bf16 v[40:43], v[188:191], v[196:199], v[40:43]
	v_mfma_f32_16x16x32_bf16 v[32:35], v[170:173], v[204:207], v[32:35]
	v_mfma_f32_16x16x32_bf16 v[24:27], v[188:191], v[204:207], v[24:27]
	v_mfma_f32_16x16x32_bf16 v[16:19], v[170:173], v[216:219], v[16:19]
	v_mfma_f32_16x16x32_bf16 v[8:11], v[188:191], v[216:219], v[8:11]
	v_mfma_f32_16x16x32_bf16 v[4:7], v[170:173], v[224:227], v[4:7]
	v_mfma_f32_16x16x32_bf16 v[0:3], v[188:191], v[224:227], v[0:3]
	s_barrier
	s_add_i32 s83, s83, 2
	s_add_u32 s12, s12, 0x100
	s_addc_u32 s13, s13, 0
	s_cmp_gt_u32 s83, 3
	s_mov_b64 s[42:43], s[44:45]
	s_cbranch_scc0 .LBB0_312
	s_and_b64 vcc, exec, s[38:39]
	s_cbranch_vccz .LBB0_315
	s_barrier

; #define PG8_STAGE(bufoff, gbase, voff) do { _Pragma("unroll") for (int _i = 0; _i < 2; ++_i) \
;         __builtin_amdgcn_global_load_lds((const unsigned*)((const char*)(gbase) + (voff)[_i]), (PG8_LAS unsigned*)(lds + (bufoff) + ldsw + _i * 8192), 16, 0, 0); } while (0)
; #define PG8_LDA(dst, b, h) do { _Pragma("unroll") for (int m = 0; m < 4; ++m) _Pragma("unroll") for (int k = 0; k < 2; ++k) dst[m][k] = *(const PG8_LAS bf16x8*)(lds + PG8_SA(b, h) + aoff + m * 2048 + k * 1024); } while (0)
; #define PG8_LDB(dst, b, h) do { _Pragma("unroll") for (int n = 0; n < 2; ++n) _Pragma("unroll") for (int k = 0; k < 2; ++k) dst[n][k] = *(const PG8_LAS bf16x8*)(lds + PG8_SB(b, h) + boff + n * 2048 + k * 1024); } while (0)
; #define PG8_MMA(ai, bj, At, Bt) do { __builtin_amdgcn_s_setprio(1); _Pragma("unroll") for (int m = 0; m < 4; ++m) _Pragma("unroll") for (int n = 0; n < 2; ++n) _Pragma("unroll") for (int k = 0; k < 2; ++k) \
;         acc[ai][bj][m][n] = __builtin_amdgcn_mfma_f32_16x16x32_bf16(Bt[n][k], At[m][k], acc[ai][bj][m][n], 0, 0, 0); __builtin_amdgcn_s_setprio(0); } while (0)
; #define PG8_WAIT_V(n) asm volatile("s_waitcnt vmcnt(" #n ")" ::: "memory")
; #define PG8_WAIT_L(n) asm volatile("s_waitcnt lgkmcnt(" #n ")" ::: "memory")
; template <class Epi, class Sched, bool ALIGN_EPI = false, bool SP2 = false>
; __device__ __forceinline__ void gemm_phase(PG8_LAS unsigned char* lds, const Gemm g, const Sched& S, const Epi& E) {
;     ...
;             const bool last = (t == nt_u - 2);
;             const char* a1 = cA + (size_t)(t + 1) * kstep;
;             const char* a2 = last ? nA : cA + (size_t)(t + 2) * kstep; const char* b2 = last ? nB : cB + (size_t)(t + 2) * kstep;
;             const char* a3 = a2 + kstep; const char* b3 = b2 + kstep;
;             if (last && has_next) S.a_ready(nxt);
;             if constexpr (SP2) {
;             PG8_LDB(B0, 0, 0); PG8_LDB(B1, 0, 1); PG8_SCHED; PG8_LDA(At, 0, 0); PG8_STAGE(PG8_SA(1, 1), a1 + hstep, voffA);
;             PG8_WAIT_V(8); PG8_WAIT_L(0); PG8_BAR; PG8_MMA(0, 0, At, B0); PG8_MMA(0, 1, At, B1); PG8_BAR; PG8_SCHED;
;             PG8_LDA(At, 0, 1); PG8_STAGE(PG8_SB(0, 0), b2, voffB); PG8_STAGE(PG8_SB(0, 1), b2 + hstep, voffB); PG8_STAGE(PG8_SA(0, 0), a2, voffA);
;             PG8_WAIT_V(8); PG8_WAIT_L(0); PG8_BAR; PG8_MMA(1, 0, At, B0); PG8_MMA(1, 1, At, B1); PG8_BAR; PG8_SCHED;
.LBB0_328:
	s_add_u32 s48, s66, s13
	s_addc_u32 s49, s67, 0
	s_add_u32 s60, s48, 0x100
	s_addc_u32 s61, s49, 0
	s_and_b64 s[20:21], s[72:73], exec
	s_cselect_b32 s77, s7, s61
	s_cselect_b32 s76, s43, s60
	s_add_u32 s13, s62, s13
	s_addc_u32 s20, s63, 0
	s_add_u32 s13, s13, 0x100
	s_addc_u32 s60, s20, 0
	s_and_b64 s[20:21], s[72:73], exec
	s_cselect_b32 s79, s41, s60
	s_cselect_b32 s78, s12, s13
	s_add_u32 s82, s48, 0x10080
	s_addc_u32 s83, s49, 0
	s_add_i32 s64, s10, s3
	ds_read_b128 v[148:151], v145
	ds_read_b128 v[152:155], v145 offset:1024
	ds_read_b128 v[156:159], v145 offset:2048
	ds_read_b128 v[160:163], v145 offset:3072
	ds_read_b128 v[164:167], v146
	ds_read_b128 v[168:171], v146 offset:1024
	ds_read_b128 v[172:175], v146 offset:2048
	ds_read_b128 v[184:187], v146 offset:3072
	s_add_i32 m0, s51, 0xc000
	s_add_i32 s65, s51, 0xe000
	s_add_i32 s49, s64, 0x2000
	s_add_u32 s80, s78, 0x10000
	s_addc_u32 s81, s79, 0
	s_add_i32 s61, s11, s3
	s_add_i32 s60, s61, 0x2000
	s_add_i32 vcc_lo, 0, 0x18000
	s_add_i32 s21, 0, 0x1c000
	s_add_u32 s74, s76, 0x10000
	s_addc_u32 s75, s77, 0
	s_add_i32 s20, vcc_lo, s3
	s_add_i32 s48, s20, 0x2000
	s_add_u32 s72, s78, 0x10080
	s_addc_u32 s73, s79, 0
	s_add_i32 vcc_hi, s21, s3
	s_add_i32 s13, vcc_hi, 0x2000
	v_lshl_add_u64 v[140:141], s[82:83], 0, v[134:135]
	ds_read_b128 v[188:191], v147
	ds_read_b128 v[192:195], v147 offset:1024
	ds_read_b128 v[196:199], v147 offset:2048
	ds_read_b128 v[200:203], v147 offset:3072
	ds_read_b128 v[204:207], v147 offset:4096
	ds_read_b128 v[212:215], v147 offset:5120
	ds_read_b128 v[216:219], v147 offset:6144
	ds_read_b128 v[220:223], v147 offset:7168
	global_load_lds_dwordx4 v[140:141], off
	v_lshl_add_u64 v[140:141], s[82:83], 0, v[130:131]
	s_mov_b32 m0, s65
	s_nop 0
	global_load_lds_dwordx4 v[140:141], off
	s_waitcnt vmcnt(8)
	s_waitcnt lgkmcnt(0)
	s_barrier
	s_waitcnt lgkmcnt(0)
	v_mfma_f32_16x16x32_bf16 v[124:127], v[148:151], v[188:191], v[124:127]
	v_mfma_f32_16x16x32_bf16 v[120:123], v[156:159], v[188:191], v[120:123]
	v_mfma_f32_16x16x32_bf16 v[116:119], v[148:151], v[196:199], v[116:119]
	v_mfma_f32_16x16x32_bf16 v[108:111], v[156:159], v[196:199], v[108:111]
	v_mfma_f32_16x16x32_bf16 v[100:103], v[148:151], v[204:207], v[100:103]
	v_mfma_f32_16x16x32_bf16 v[92:95], v[156:159], v[204:207], v[92:95]
	v_mfma_f32_16x16x32_bf16 v[84:87], v[148:151], v[216:219], v[84:87]
	v_mfma_f32_16x16x32_bf16 v[76:79], v[156:159], v[216:219], v[76:79]
	v_mfma_f32_16x16x32_bf16 v[124:127], v[152:155], v[192:195], v[124:127]
	v_mfma_f32_16x16x32_bf16 v[120:123], v[160:163], v[192:195], v[120:123]
	v_mfma_f32_16x16x32_bf16 v[116:119], v[152:155], v[200:203], v[116:119]
	v_mfma_f32_16x16x32_bf16 v[108:111], v[160:163], v[200:203], v[108:111]
	v_mfma_f32_16x16x32_bf16 v[100:103], v[152:155], v[212:215], v[100:103]
	v_mfma_f32_16x16x32_bf16 v[92:95], v[160:163], v[212:215], v[92:95]
	v_mfma_f32_16x16x32_bf16 v[84:87], v[152:155], v[220:223], v[84:87]
	v_mfma_f32_16x16x32_bf16 v[76:79], v[160:163], v[220:223], v[76:79]
	v_mfma_f32_16x16x32_bf16 v[112:115], v[164:167], v[188:191], v[112:115]
	v_mfma_f32_16x16x32_bf16 v[104:107], v[172:175], v[188:191], v[104:107]
	v_mfma_f32_16x16x32_bf16 v[96:99], v[164:167], v[196:199], v[96:99]
	v_mfma_f32_16x16x32_bf16 v[88:91], v[172:175], v[196:199], v[88:91]
	v_mfma_f32_16x16x32_bf16 v[80:83], v[164:167], v[204:207], v[80:83]
	v_mfma_f32_16x16x32_bf16 v[72:75], v[172:175], v[204:207], v[72:75]
	v_mfma_f32_16x16x32_bf16 v[68:71], v[164:167], v[216:219], v[68:71]
	v_mfma_f32_16x16x32_bf16 v[64:67], v[172:175], v[216:219], v[64:67]
	v_mfma_f32_16x16x32_bf16 v[112:115], v[168:171], v[192:195], v[112:115]
	v_mfma_f32_16x16x32_bf16 v[104:107], v[184:187], v[192:195], v[104:107]
	v_mfma_f32_16x16x32_bf16 v[96:99], v[168:171], v[200:203], v[96:99]
	v_mfma_f32_16x16x32_bf16 v[88:91], v[184:187], v[200:203], v[88:91]
	v_mfma_f32_16x16x32_bf16 v[80:83], v[168:171], v[212:215], v[80:83]
	v_mfma_f32_16x16x32_bf16 v[72:75], v[184:187], v[212:215], v[72:75]
	v_mfma_f32_16x16x32_bf16 v[68:71], v[168:171], v[220:223], v[68:71]
	v_mfma_f32_16x16x32_bf16 v[64:67], v[184:187], v[220:223], v[64:67]
	s_barrier
	s_mov_b32 m0, s64
	v_lshl_add_u64 v[140:141], s[78:79], 0, v[132:133]
	ds_read_b128 v[188:191], v147 offset:16384
	ds_read_b128 v[192:195], v147 offset:17408
	ds_read_b128 v[196:199], v147 offset:18432
	ds_read_b128 v[200:203], v147 offset:19456
	ds_read_b128 v[204:207], v147 offset:20480
	ds_read_b128 v[212:215], v147 offset:21504
	ds_read_b128 v[216:219], v147 offset:22528
	ds_read_b128 v[220:223], v147 offset:23552
	global_load_lds_dwordx4 v[140:141], off
	v_lshl_add_u64 v[208:209], s[78:79], 0, v[128:129]
	s_mov_b32 m0, s49
	v_lshl_add_u64 v[224:225], s[80:81], 0, v[132:133]
	global_load_lds_dwordx4 v[208:209], off
	s_mov_b32 m0, s61
	v_lshl_add_u64 v[226:227], s[76:77], 0, v[130:131]
	global_load_lds_dwordx4 v[224:225], off
	v_lshl_add_u64 v[224:225], s[80:81], 0, v[128:129]
	s_mov_b32 m0, s60
	s_nop 0
	global_load_lds_dwordx4 v[224:225], off
	v_lshl_add_u64 v[224:225], s[76:77], 0, v[134:135]
	s_mov_b32 m0, s51
	s_nop 0
	global_load_lds_dwordx4 v[224:225], off
	s_mov_b32 m0, s91
	s_nop 0
	global_load_lds_dwordx4 v[226:227], off
	s_waitcnt vmcnt(8)
	s_waitcnt lgkmcnt(0)
	s_barrier
; #define PG8_STAGE(bufoff, gbase, voff) do { _Pragma("unroll") for (int _i = 0; _i < 2; ++_i) \
;         __builtin_amdgcn_global_load_lds((const unsigned*)((const char*)(gbase) + (voff)[_i]), (PG8_LAS unsigned*)(lds + (bufoff) + ldsw + _i * 8192), 16, 0, 0); } while (0)
; #define PG8_LDA(dst, b, h) do { _Pragma("unroll") for (int m = 0; m < 4; ++m) _Pragma("unroll") for (int k = 0; k < 2; ++k) dst[m][k] = *(const PG8_LAS bf16x8*)(lds + PG8_SA(b, h) + aoff + m * 2048 + k * 1024); } while (0)
; #define PG8_LDB(dst, b, h) do { _Pragma("unroll") for (int n = 0; n < 2; ++n) _Pragma("unroll") for (int k = 0; k < 2; ++k) dst[n][k] = *(const PG8_LAS bf16x8*)(lds + PG8_SB(b, h) + boff + n * 2048 + k * 1024); } while (0)
; #define PG8_MMA(ai, bj, At, Bt) do { __builtin_amdgcn_s_setprio(1); _Pragma("unroll") for (int m = 0; m < 4; ++m) _Pragma("unroll") for (int n = 0; n < 2; ++n) _Pragma("unroll") for (int k = 0; k < 2; ++k) \
;         acc[ai][bj][m][n] = __builtin_amdgcn_mfma_f32_16x16x32_bf16(Bt[n][k], At[m][k], acc[ai][bj][m][n], 0, 0, 0); __builtin_amdgcn_s_setprio(0); } while (0)
; #define PG8_WAIT_V(n) asm volatile("s_waitcnt vmcnt(" #n ")" ::: "memory")
; #define PG8_WAIT_L(n) asm volatile("s_waitcnt lgkmcnt(" #n ")" ::: "memory")
; #define PG8_BAR __builtin_amdgcn_s_barrier()
; #define PG8_SCHED __builtin_amdgcn_sched_barrier(0)
; template <class Epi, class Sched, bool ALIGN_EPI = false, bool SP2 = false>
; __device__ __forceinline__ void gemm_phase(PG8_LAS unsigned char* lds, const Gemm g, const Sched& S, const Epi& E) {
;     ...
;             PG8_WAIT_V(8); PG8_WAIT_L(0); PG8_BAR; PG8_MMA(1, 0, At, B0); PG8_MMA(1, 1, At, B1); PG8_BAR; PG8_SCHED;
;             PG8_LDB(B0, 1, 0); PG8_LDB(B1, 1, 1); PG8_SCHED; PG8_LDA(At, 1, 0); PG8_STAGE(PG8_SA(0, 1), a2 + hstep, voffA);
;             PG8_WAIT_V(8); PG8_WAIT_L(0); PG8_BAR; PG8_MMA(0, 0, At, B0); PG8_MMA(0, 1, At, B1); PG8_BAR; PG8_SCHED;
	s_waitcnt lgkmcnt(0)
	v_mfma_f32_16x16x32_bf16 v[60:63], v[148:151], v[188:191], v[60:63]
	v_mfma_f32_16x16x32_bf16 v[56:59], v[156:159], v[188:191], v[56:59]
	v_mfma_f32_16x16x32_bf16 v[52:55], v[148:151], v[196:199], v[52:55]
	v_mfma_f32_16x16x32_bf16 v[44:47], v[156:159], v[196:199], v[44:47]
	v_mfma_f32_16x16x32_bf16 v[36:39], v[148:151], v[204:207], v[36:39]
	v_mfma_f32_16x16x32_bf16 v[28:31], v[156:159], v[204:207], v[28:31]
	v_mfma_f32_16x16x32_bf16 v[20:23], v[148:151], v[216:219], v[20:23]
	v_mfma_f32_16x16x32_bf16 v[12:15], v[156:159], v[216:219], v[12:15]
	v_mfma_f32_16x16x32_bf16 v[60:63], v[152:155], v[192:195], v[60:63]
	v_mfma_f32_16x16x32_bf16 v[56:59], v[160:163], v[192:195], v[56:59]
	v_mfma_f32_16x16x32_bf16 v[52:55], v[152:155], v[200:203], v[52:55]
	v_mfma_f32_16x16x32_bf16 v[44:47], v[160:163], v[200:203], v[44:47]
	v_mfma_f32_16x16x32_bf16 v[36:39], v[152:155], v[212:215], v[36:39]
	v_mfma_f32_16x16x32_bf16 v[28:31], v[160:163], v[212:215], v[28:31]
	v_mfma_f32_16x16x32_bf16 v[20:23], v[152:155], v[220:223], v[20:23]
	v_mfma_f32_16x16x32_bf16 v[12:15], v[160:163], v[220:223], v[12:15]
	v_mfma_f32_16x16x32_bf16 v[48:51], v[164:167], v[188:191], v[48:51]
	v_mfma_f32_16x16x32_bf16 v[40:43], v[172:175], v[188:191], v[40:43]
	v_mfma_f32_16x16x32_bf16 v[32:35], v[164:167], v[196:199], v[32:35]
	v_mfma_f32_16x16x32_bf16 v[24:27], v[172:175], v[196:199], v[24:27]
	v_mfma_f32_16x16x32_bf16 v[16:19], v[164:167], v[204:207], v[16:19]
	v_mfma_f32_16x16x32_bf16 v[8:11], v[172:175], v[204:207], v[8:11]
	v_mfma_f32_16x16x32_bf16 v[4:7], v[164:167], v[216:219], v[4:7]
	v_mfma_f32_16x16x32_bf16 v[0:3], v[172:175], v[216:219], v[0:3]
	v_mfma_f32_16x16x32_bf16 v[48:51], v[168:171], v[192:195], v[48:51]
	v_mfma_f32_16x16x32_bf16 v[40:43], v[184:187], v[192:195], v[40:43]
	v_mfma_f32_16x16x32_bf16 v[32:35], v[168:171], v[200:203], v[32:35]
	v_mfma_f32_16x16x32_bf16 v[24:27], v[184:187], v[200:203], v[24:27]
	v_mfma_f32_16x16x32_bf16 v[16:19], v[168:171], v[212:215], v[16:19]
	v_mfma_f32_16x16x32_bf16 v[8:11], v[184:187], v[212:215], v[8:11]
	v_mfma_f32_16x16x32_bf16 v[4:7], v[168:171], v[220:223], v[4:7]
	v_mfma_f32_16x16x32_bf16 v[0:3], v[184:187], v[220:223], v[0:3]
	s_barrier
	v_add_u32_e32 v160, vcc_lo, v143
	v_add_u32_e32 v177, s21, v143
	ds_read_b128 v[148:151], v160
	ds_read_b128 v[152:155], v160 offset:1024
	ds_read_b128 v[156:159], v160 offset:2048
	ds_read_b128 v[160:163], v160 offset:3072
	ds_read_b128 v[164:167], v177
	ds_read_b128 v[168:171], v177 offset:1024
	ds_read_b128 v[172:175], v177 offset:2048
	ds_read_b128 v[184:187], v177 offset:3072
	s_mov_b32 m0, s92
	v_lshl_add_u64 v[228:229], s[74:75], 0, v[134:135]
	ds_read_b128 v[188:191], v147 offset:32768
	ds_read_b128 v[192:195], v147 offset:33792
	ds_read_b128 v[196:199], v147 offset:34816
	ds_read_b128 v[200:203], v147 offset:35840
	ds_read_b128 v[204:207], v147 offset:36864
	ds_read_b128 v[212:215], v147 offset:37888
	ds_read_b128 v[216:219], v147 offset:38912
	ds_read_b128 v[220:223], v147 offset:39936
	global_load_lds_dwordx4 v[228:229], off
	v_lshl_add_u64 v[228:229], s[74:75], 0, v[130:131]
	s_mov_b32 m0, s93
	s_nop 0
	global_load_lds_dwordx4 v[228:229], off
	s_waitcnt vmcnt(8)
	s_waitcnt lgkmcnt(0)
	s_barrier
	s_waitcnt lgkmcnt(0)
	v_mfma_f32_16x16x32_bf16 v[124:127], v[148:151], v[188:191], v[124:127]
	v_mfma_f32_16x16x32_bf16 v[120:123], v[156:159], v[188:191], v[120:123]
	v_mfma_f32_16x16x32_bf16 v[116:119], v[148:151], v[196:199], v[116:119]
	v_mfma_f32_16x16x32_bf16 v[108:111], v[156:159], v[196:199], v[108:111]
	v_mfma_f32_16x16x32_bf16 v[100:103], v[148:151], v[204:207], v[100:103]
	v_mfma_f32_16x16x32_bf16 v[92:95], v[156:159], v[204:207], v[92:95]
	v_mfma_f32_16x16x32_bf16 v[84:87], v[148:151], v[216:219], v[84:87]
	v_mfma_f32_16x16x32_bf16 v[76:79], v[156:159], v[216:219], v[76:79]
	v_mfma_f32_16x16x32_bf16 v[124:127], v[152:155], v[192:195], v[124:127]
	v_mfma_f32_16x16x32_bf16 v[120:123], v[160:163], v[192:195], v[120:123]
	v_mfma_f32_16x16x32_bf16 v[116:119], v[152:155], v[200:203], v[116:119]
	v_mfma_f32_16x16x32_bf16 v[108:111], v[160:163], v[200:203], v[108:111]
	v_mfma_f32_16x16x32_bf16 v[100:103], v[152:155], v[212:215], v[100:103]
	v_mfma_f32_16x16x32_bf16 v[92:95], v[160:163], v[212:215], v[92:95]
	v_mfma_f32_16x16x32_bf16 v[84:87], v[152:155], v[220:223], v[84:87]
	v_mfma_f32_16x16x32_bf16 v[76:79], v[160:163], v[220:223], v[76:79]
	v_mfma_f32_16x16x32_bf16 v[112:115], v[164:167], v[188:191], v[112:115]
	v_mfma_f32_16x16x32_bf16 v[104:107], v[172:175], v[188:191], v[104:107]
	v_mfma_f32_16x16x32_bf16 v[96:99], v[164:167], v[196:199], v[96:99]
	v_mfma_f32_16x16x32_bf16 v[88:91], v[172:175], v[196:199], v[88:91]
	v_mfma_f32_16x16x32_bf16 v[80:83], v[164:167], v[204:207], v[80:83]
	v_mfma_f32_16x16x32_bf16 v[72:75], v[172:175], v[204:207], v[72:75]
	v_mfma_f32_16x16x32_bf16 v[68:71], v[164:167], v[216:219], v[68:71]
	v_mfma_f32_16x16x32_bf16 v[64:67], v[172:175], v[216:219], v[64:67]
	v_mfma_f32_16x16x32_bf16 v[112:115], v[168:171], v[192:195], v[112:115]
	v_mfma_f32_16x16x32_bf16 v[104:107], v[184:187], v[192:195], v[104:107]
	v_mfma_f32_16x16x32_bf16 v[96:99], v[168:171], v[200:203], v[96:99]
	v_mfma_f32_16x16x32_bf16 v[88:91], v[184:187], v[200:203], v[88:91]
	v_mfma_f32_16x16x32_bf16 v[80:83], v[168:171], v[212:215], v[80:83]
	v_mfma_f32_16x16x32_bf16 v[72:75], v[184:187], v[212:215], v[72:75]
	v_mfma_f32_16x16x32_bf16 v[68:71], v[168:171], v[220:223], v[68:71]
	v_mfma_f32_16x16x32_bf16 v[64:67], v[184:187], v[220:223], v[64:67]
	s_barrier
; #define PG8_STAGE(bufoff, gbase, voff) do { _Pragma("unroll") for (int _i = 0; _i < 2; ++_i) \
;         __builtin_amdgcn_global_load_lds((const unsigned*)((const char*)(gbase) + (voff)[_i]), (PG8_LAS unsigned*)(lds + (bufoff) + ldsw + _i * 8192), 16, 0, 0); } while (0)
; #define PG8_LDA(dst, b, h) do { _Pragma("unroll") for (int m = 0; m < 4; ++m) _Pragma("unroll") for (int k = 0; k < 2; ++k) dst[m][k] = *(const PG8_LAS bf16x8*)(lds + PG8_SA(b, h) + aoff + m * 2048 + k * 1024); } while (0)
; #define PG8_MMA(ai, bj, At, Bt) do { __builtin_amdgcn_s_setprio(1); _Pragma("unroll") for (int m = 0; m < 4; ++m) _Pragma("unroll") for (int n = 0; n < 2; ++n) _Pragma("unroll") for (int k = 0; k < 2; ++k) \
;         acc[ai][bj][m][n] = __builtin_amdgcn_mfma_f32_16x16x32_bf16(Bt[n][k], At[m][k], acc[ai][bj][m][n], 0, 0, 0); __builtin_amdgcn_s_setprio(0); } while (0)
; #define PG8_WAIT_V(n) asm volatile("s_waitcnt vmcnt(" #n ")" ::: "memory")
; #define PG8_WAIT_L(n) asm volatile("s_waitcnt lgkmcnt(" #n ")" ::: "memory")
; #define PG8_BAR __builtin_amdgcn_s_barrier()
; #define PG8_SCHED __builtin_amdgcn_sched_barrier(0)
; template <class Epi, class Sched, bool ALIGN_EPI = false, bool SP2 = false>
; __device__ __forceinline__ void gemm_phase(PG8_LAS unsigned char* lds, const Gemm g, const Sched& S, const Epi& E) {
;     ...
;             PG8_LDA(At, 1, 1); PG8_STAGE(PG8_SB(1, 0), b3, voffB); PG8_STAGE(PG8_SB(1, 1), b3 + hstep, voffB); PG8_STAGE(PG8_SA(1, 0), a3, voffA);
;             PG8_WAIT_V(8); PG8_WAIT_L(0); PG8_BAR; PG8_MMA(1, 0, At, B0); PG8_MMA(1, 1, At, B1); PG8_BAR; PG8_SCHED;
	s_mov_b32 m0, s20
	v_lshl_add_u64 v[140:141], v[140:141], 0, s[36:37]
	ds_read_b128 v[188:191], v147 offset:49152
	ds_read_b128 v[192:195], v147 offset:50176
	ds_read_b128 v[196:199], v147 offset:51200
	ds_read_b128 v[200:203], v147 offset:52224
	ds_read_b128 v[204:207], v147 offset:53248
	ds_read_b128 v[212:215], v147 offset:54272
	ds_read_b128 v[216:219], v147 offset:55296
	ds_read_b128 v[220:223], v147 offset:56320
	global_load_lds_dwordx4 v[140:141], off
	v_lshl_add_u64 v[140:141], v[208:209], 0, s[36:37]
	s_mov_b32 m0, s48
	s_nop 0
	global_load_lds_dwordx4 v[140:141], off
	v_lshl_add_u64 v[140:141], s[72:73], 0, v[132:133]
	s_mov_b32 m0, vcc_hi
	s_nop 0
	global_load_lds_dwordx4 v[140:141], off
	v_lshl_add_u64 v[140:141], s[72:73], 0, v[128:129]
	s_mov_b32 m0, s13
	s_nop 0
	global_load_lds_dwordx4 v[140:141], off
	v_lshl_add_u64 v[140:141], v[224:225], 0, s[36:37]
	s_mov_b32 m0, s95
	s_nop 0
	global_load_lds_dwordx4 v[140:141], off
	v_lshl_add_u64 v[140:141], v[226:227], 0, s[36:37]
	s_mov_b32 m0, s96
	s_nop 0
	global_load_lds_dwordx4 v[140:141], off
	s_waitcnt vmcnt(8)
	s_waitcnt lgkmcnt(0)
	s_barrier
	s_waitcnt lgkmcnt(0)
	v_mfma_f32_16x16x32_bf16 v[60:63], v[148:151], v[188:191], v[60:63]
	v_mfma_f32_16x16x32_bf16 v[56:59], v[156:159], v[188:191], v[56:59]
	v_mfma_f32_16x16x32_bf16 v[52:55], v[148:151], v[196:199], v[52:55]
	v_mfma_f32_16x16x32_bf16 v[44:47], v[156:159], v[196:199], v[44:47]
	v_mfma_f32_16x16x32_bf16 v[36:39], v[148:151], v[204:207], v[36:39]
	v_mfma_f32_16x16x32_bf16 v[28:31], v[156:159], v[204:207], v[28:31]
	v_mfma_f32_16x16x32_bf16 v[20:23], v[148:151], v[216:219], v[20:23]
	v_mfma_f32_16x16x32_bf16 v[12:15], v[156:159], v[216:219], v[12:15]
	v_mfma_f32_16x16x32_bf16 v[60:63], v[152:155], v[192:195], v[60:63]
	v_mfma_f32_16x16x32_bf16 v[56:59], v[160:163], v[192:195], v[56:59]
	v_mfma_f32_16x16x32_bf16 v[52:55], v[152:155], v[200:203], v[52:55]
	v_mfma_f32_16x16x32_bf16 v[44:47], v[160:163], v[200:203], v[44:47]
	v_mfma_f32_16x16x32_bf16 v[36:39], v[152:155], v[212:215], v[36:39]
	v_mfma_f32_16x16x32_bf16 v[28:31], v[160:163], v[212:215], v[28:31]
	v_mfma_f32_16x16x32_bf16 v[20:23], v[152:155], v[220:223], v[20:23]
	v_mfma_f32_16x16x32_bf16 v[12:15], v[160:163], v[220:223], v[12:15]
	v_mfma_f32_16x16x32_bf16 v[48:51], v[164:167], v[188:191], v[48:51]
	v_mfma_f32_16x16x32_bf16 v[40:43], v[172:175], v[188:191], v[40:43]
	v_mfma_f32_16x16x32_bf16 v[32:35], v[164:167], v[196:199], v[32:35]
	v_mfma_f32_16x16x32_bf16 v[24:27], v[172:175], v[196:199], v[24:27]
	v_mfma_f32_16x16x32_bf16 v[16:19], v[164:167], v[204:207], v[16:19]
	v_mfma_f32_16x16x32_bf16 v[8:11], v[172:175], v[204:207], v[8:11]
	v_mfma_f32_16x16x32_bf16 v[4:7], v[164:167], v[216:219], v[4:7]
	v_mfma_f32_16x16x32_bf16 v[0:3], v[172:175], v[216:219], v[0:3]
	v_mfma_f32_16x16x32_bf16 v[48:51], v[168:171], v[192:195], v[48:51]
	v_mfma_f32_16x16x32_bf16 v[40:43], v[184:187], v[192:195], v[40:43]
	v_mfma_f32_16x16x32_bf16 v[32:35], v[168:171], v[200:203], v[32:35]
	v_mfma_f32_16x16x32_bf16 v[24:27], v[184:187], v[200:203], v[24:27]
	v_mfma_f32_16x16x32_bf16 v[16:19], v[168:171], v[212:215], v[16:19]
	v_mfma_f32_16x16x32_bf16 v[8:11], v[184:187], v[212:215], v[8:11]
	v_mfma_f32_16x16x32_bf16 v[4:7], v[168:171], v[220:223], v[4:7]
	v_mfma_f32_16x16x32_bf16 v[0:3], v[184:187], v[220:223], v[0:3]
	s_barrier
	s_movk_i32 s13, 0x100
	s_andn2_b64 vcc, exec, s[70:71]
	s_mov_b64 s[72:73], -1
	s_mov_b64 s[70:71], 0
	s_cbranch_vccz .LBB0_328
	s_and_b64 vcc, exec, s[38:39]
	s_cbranch_vccz .LBB0_331
	s_barrier

; #define PG8_STAGE(bufoff, gbase, voff) do { _Pragma("unroll") for (int _i = 0; _i < 2; ++_i) \
;         __builtin_amdgcn_global_load_lds((const unsigned*)((const char*)(gbase) + (voff)[_i]), (PG8_LAS unsigned*)(lds + (bufoff) + ldsw + _i * 8192), 16, 0, 0); } while (0)
; #define PG8_LDA(dst, b, h) do { _Pragma("unroll") for (int m = 0; m < 4; ++m) _Pragma("unroll") for (int k = 0; k < 2; ++k) dst[m][k] = *(const PG8_LAS bf16x8*)(lds + PG8_SA(b, h) + aoff + m * 2048 + k * 1024); } while (0)
; #define PG8_LDB(dst, b, h) do { _Pragma("unroll") for (int n = 0; n < 2; ++n) _Pragma("unroll") for (int k = 0; k < 2; ++k) dst[n][k] = *(const PG8_LAS bf16x8*)(lds + PG8_SB(b, h) + boff + n * 2048 + k * 1024); } while (0)
; #define PG8_MMA(ai, bj, At, Bt) do { __builtin_amdgcn_s_setprio(1); _Pragma("unroll") for (int m = 0; m < 4; ++m) _Pragma("unroll") for (int n = 0; n < 2; ++n) _Pragma("unroll") for (int k = 0; k < 2; ++k) \
;         acc[ai][bj][m][n] = __builtin_amdgcn_mfma_f32_16x16x32_bf16(Bt[n][k], At[m][k], acc[ai][bj][m][n], 0, 0, 0); __builtin_amdgcn_s_setprio(0); } while (0)
; #define PG8_WAIT_V(n) asm volatile("s_waitcnt vmcnt(" #n ")" ::: "memory")
; #define PG8_BAR __builtin_amdgcn_s_barrier()
; template <class Epi, class Sched, bool ALIGN_EPI = false, bool SP2 = false>
; __device__ __forceinline__ void gemm_phase(PG8_LAS unsigned char* lds, const Gemm g, const Sched& S, const Epi& E) {
;     ...
;         for (int t = 0; t < nt_u; t += 2) {
;             const bool last = (t == nt_u - 2);
;             const char* a1 = cA + (size_t)(t + 1) * kstep;
;             const char* a2 = last ? nA : cA + (size_t)(t + 2) * kstep; const char* b2 = last ? nB : cB + (size_t)(t + 2) * kstep;
;             const char* a3 = a2 + kstep; const char* b3 = b2 + kstep;
;             if (last && has_next) S.a_ready(nxt);
;             if constexpr (SP2) {
;             PG8_LDB(B0, 0, 0); PG8_LDB(B1, 0, 1); PG8_SCHED; PG8_LDA(At, 0, 0); PG8_STAGE(PG8_SA(1, 1), a1 + hstep, voffA);
;             PG8_WAIT_V(8); PG8_WAIT_L(0); PG8_BAR; PG8_MMA(0, 0, At, B0); PG8_MMA(0, 1, At, B1); PG8_BAR; PG8_SCHED;
;             PG8_LDA(At, 0, 1); PG8_STAGE(PG8_SB(0, 0), b2, voffB); PG8_STAGE(PG8_SB(0, 1), b2 + hstep, voffB); PG8_STAGE(PG8_SA(0, 0), a2, voffA);
;             PG8_WAIT_V(8); PG8_WAIT_L(0); PG8_BAR; PG8_MMA(1, 0, At, B0); PG8_MMA(1, 1, At, B1); PG8_BAR; PG8_SCHED;
.LBB0_543:
	ds_read_b128 v[128:131], v163
	ds_read_b128 v[132:135], v163 offset:1024
	ds_read_b128 v[136:139], v163 offset:2048
	ds_read_b128 v[140:143], v163 offset:3072
	ds_read_b128 v[156:159], v164
	ds_read_b128 v[166:169], v164 offset:1024
	ds_read_b128 v[170:173], v164 offset:2048
	ds_read_b128 v[182:185], v164 offset:3072
	s_add_u32 s20, s46, 0xfffc0080
	s_addc_u32 s21, s47, -1
	s_cmp_eq_u32 s79, 12
	s_cselect_b32 s51, s12, s21
	s_cselect_b32 s50, s13, s20
	s_cselect_b32 s49, s37, s78
	s_cselect_b32 s48, s39, s45
	v_lshl_add_u64 v[174:175], s[46:47], 0, v[148:149]
	s_add_i32 m0, s63, 0xc000
	ds_read_b128 v[186:189], v165
	ds_read_b128 v[190:193], v165 offset:1024
	ds_read_b128 v[194:197], v165 offset:2048
	ds_read_b128 v[198:201], v165 offset:3072
	ds_read_b128 v[202:205], v165 offset:4096
	ds_read_b128 v[206:209], v165 offset:5120
	ds_read_b128 v[212:215], v165 offset:6144
	ds_read_b128 v[216:219], v165 offset:7168
	global_load_lds_dwordx4 v[174:175], off
	v_lshl_add_u64 v[174:175], s[46:47], 0, v[150:151]
	s_add_i32 m0, s63, 0xe000
	s_nop 0
	global_load_lds_dwordx4 v[174:175], off
	s_waitcnt vmcnt(8)
	s_waitcnt lgkmcnt(0)
	s_barrier
	s_waitcnt lgkmcnt(0)
	v_mfma_f32_16x16x32_bf16 v[124:127], v[128:131], v[186:189], v[124:127]
	v_mfma_f32_16x16x32_bf16 v[120:123], v[136:139], v[186:189], v[120:123]
	v_mfma_f32_16x16x32_bf16 v[112:115], v[128:131], v[194:197], v[112:115]
	v_mfma_f32_16x16x32_bf16 v[108:111], v[136:139], v[194:197], v[108:111]
	v_mfma_f32_16x16x32_bf16 v[96:99], v[128:131], v[202:205], v[96:99]
	v_mfma_f32_16x16x32_bf16 v[92:95], v[136:139], v[202:205], v[92:95]
	v_mfma_f32_16x16x32_bf16 v[80:83], v[128:131], v[212:215], v[80:83]
	v_mfma_f32_16x16x32_bf16 v[76:79], v[136:139], v[212:215], v[76:79]
	v_mfma_f32_16x16x32_bf16 v[124:127], v[132:135], v[190:193], v[124:127]
	v_mfma_f32_16x16x32_bf16 v[120:123], v[140:143], v[190:193], v[120:123]
	v_mfma_f32_16x16x32_bf16 v[112:115], v[132:135], v[198:201], v[112:115]
	v_mfma_f32_16x16x32_bf16 v[108:111], v[140:143], v[198:201], v[108:111]
	v_mfma_f32_16x16x32_bf16 v[96:99], v[132:135], v[206:209], v[96:99]
	v_mfma_f32_16x16x32_bf16 v[92:95], v[140:143], v[206:209], v[92:95]
	v_mfma_f32_16x16x32_bf16 v[80:83], v[132:135], v[216:219], v[80:83]
	v_mfma_f32_16x16x32_bf16 v[76:79], v[140:143], v[216:219], v[76:79]
	v_mfma_f32_16x16x32_bf16 v[116:119], v[156:159], v[186:189], v[116:119]
	v_mfma_f32_16x16x32_bf16 v[104:107], v[170:173], v[186:189], v[104:107]
	v_mfma_f32_16x16x32_bf16 v[100:103], v[156:159], v[194:197], v[100:103]
	v_mfma_f32_16x16x32_bf16 v[88:91], v[170:173], v[194:197], v[88:91]
	v_mfma_f32_16x16x32_bf16 v[84:87], v[156:159], v[202:205], v[84:87]
	v_mfma_f32_16x16x32_bf16 v[72:75], v[170:173], v[202:205], v[72:75]
	v_mfma_f32_16x16x32_bf16 v[68:71], v[156:159], v[212:215], v[68:71]
	v_mfma_f32_16x16x32_bf16 v[64:67], v[170:173], v[212:215], v[64:67]
	v_mfma_f32_16x16x32_bf16 v[116:119], v[166:169], v[190:193], v[116:119]
	v_mfma_f32_16x16x32_bf16 v[104:107], v[182:185], v[190:193], v[104:107]
	v_mfma_f32_16x16x32_bf16 v[100:103], v[166:169], v[198:201], v[100:103]
	v_mfma_f32_16x16x32_bf16 v[88:91], v[182:185], v[198:201], v[88:91]
	v_mfma_f32_16x16x32_bf16 v[84:87], v[166:169], v[206:209], v[84:87]
	v_mfma_f32_16x16x32_bf16 v[72:75], v[182:185], v[206:209], v[72:75]
	v_mfma_f32_16x16x32_bf16 v[68:71], v[166:169], v[216:219], v[68:71]
	v_mfma_f32_16x16x32_bf16 v[64:67], v[182:185], v[216:219], v[64:67]
	s_barrier
	s_add_i32 s20, s75, s3
	v_lshl_add_u64 v[174:175], s[48:49], 0, v[146:147]
	s_mov_b32 m0, s20
	ds_read_b128 v[186:189], v165 offset:16384
	ds_read_b128 v[190:193], v165 offset:17408
	ds_read_b128 v[194:197], v165 offset:18432
	ds_read_b128 v[198:201], v165 offset:19456
	ds_read_b128 v[202:205], v165 offset:20480
	ds_read_b128 v[206:209], v165 offset:21504
	ds_read_b128 v[212:215], v165 offset:22528
	ds_read_b128 v[216:219], v165 offset:23552
	global_load_lds_dwordx4 v[174:175], off
	s_add_i32 m0, s20, 0x2000
	s_add_u32 s20, s48, 0x40000
	v_lshl_add_u64 v[220:221], s[48:49], 0, v[144:145]
	s_addc_u32 s21, s49, 0
	s_add_i32 s60, s76, s3
	global_load_lds_dwordx4 v[220:221], off
	v_lshl_add_u64 v[222:223], s[20:21], 0, v[146:147]
	s_mov_b32 m0, s60
	v_lshl_add_u64 v[224:225], s[50:51], 0, v[144:145]
	global_load_lds_dwordx4 v[222:223], off
	v_lshl_add_u64 v[222:223], s[20:21], 0, v[144:145]
	s_add_i32 m0, s60, 0x2000
	s_nop 0
	global_load_lds_dwordx4 v[222:223], off
	v_lshl_add_u64 v[222:223], s[50:51], 0, v[146:147]
	s_mov_b32 m0, s63
	s_nop 0
	global_load_lds_dwordx4 v[222:223], off
	s_mov_b32 m0, s66
	s_nop 0
	global_load_lds_dwordx4 v[224:225], off
	s_waitcnt vmcnt(8)
	s_waitcnt lgkmcnt(0)
	s_barrier
; #define PG8_STAGE(bufoff, gbase, voff) do { _Pragma("unroll") for (int _i = 0; _i < 2; ++_i) \
;         __builtin_amdgcn_global_load_lds((const unsigned*)((const char*)(gbase) + (voff)[_i]), (PG8_LAS unsigned*)(lds + (bufoff) + ldsw + _i * 8192), 16, 0, 0); } while (0)
; #define PG8_LDA(dst, b, h) do { _Pragma("unroll") for (int m = 0; m < 4; ++m) _Pragma("unroll") for (int k = 0; k < 2; ++k) dst[m][k] = *(const PG8_LAS bf16x8*)(lds + PG8_SA(b, h) + aoff + m * 2048 + k * 1024); } while (0)
; #define PG8_LDB(dst, b, h) do { _Pragma("unroll") for (int n = 0; n < 2; ++n) _Pragma("unroll") for (int k = 0; k < 2; ++k) dst[n][k] = *(const PG8_LAS bf16x8*)(lds + PG8_SB(b, h) + boff + n * 2048 + k * 1024); } while (0)
; #define PG8_MMA(ai, bj, At, Bt) do { __builtin_amdgcn_s_setprio(1); _Pragma("unroll") for (int m = 0; m < 4; ++m) _Pragma("unroll") for (int n = 0; n < 2; ++n) _Pragma("unroll") for (int k = 0; k < 2; ++k) \
;         acc[ai][bj][m][n] = __builtin_amdgcn_mfma_f32_16x16x32_bf16(Bt[n][k], At[m][k], acc[ai][bj][m][n], 0, 0, 0); __builtin_amdgcn_s_setprio(0); } while (0)
; #define PG8_WAIT_V(n) asm volatile("s_waitcnt vmcnt(" #n ")" ::: "memory")
; #define PG8_WAIT_L(n) asm volatile("s_waitcnt lgkmcnt(" #n ")" ::: "memory")
; #define PG8_BAR __builtin_amdgcn_s_barrier()
; #define PG8_SCHED __builtin_amdgcn_sched_barrier(0)
; template <class Epi, class Sched, bool ALIGN_EPI = false, bool SP2 = false>
; __device__ __forceinline__ void gemm_phase(PG8_LAS unsigned char* lds, const Gemm g, const Sched& S, const Epi& E) {
;     ...
;             PG8_WAIT_V(8); PG8_WAIT_L(0); PG8_BAR; PG8_MMA(1, 0, At, B0); PG8_MMA(1, 1, At, B1); PG8_BAR; PG8_SCHED;
;             PG8_LDB(B0, 1, 0); PG8_LDB(B1, 1, 1); PG8_SCHED; PG8_LDA(At, 1, 0); PG8_STAGE(PG8_SA(0, 1), a2 + hstep, voffA);
;             PG8_WAIT_V(8); PG8_WAIT_L(0); PG8_BAR; PG8_MMA(0, 0, At, B0); PG8_MMA(0, 1, At, B1); PG8_BAR; PG8_SCHED;
	s_waitcnt lgkmcnt(0)
	v_mfma_f32_16x16x32_bf16 v[60:63], v[128:131], v[186:189], v[60:63]
	v_mfma_f32_16x16x32_bf16 v[56:59], v[136:139], v[186:189], v[56:59]
	v_mfma_f32_16x16x32_bf16 v[48:51], v[128:131], v[194:197], v[48:51]
	v_mfma_f32_16x16x32_bf16 v[44:47], v[136:139], v[194:197], v[44:47]
	v_mfma_f32_16x16x32_bf16 v[32:35], v[128:131], v[202:205], v[32:35]
	v_mfma_f32_16x16x32_bf16 v[28:31], v[136:139], v[202:205], v[28:31]
	v_mfma_f32_16x16x32_bf16 v[16:19], v[128:131], v[212:215], v[16:19]
	v_mfma_f32_16x16x32_bf16 v[12:15], v[136:139], v[212:215], v[12:15]
	v_mfma_f32_16x16x32_bf16 v[60:63], v[132:135], v[190:193], v[60:63]
	v_mfma_f32_16x16x32_bf16 v[56:59], v[140:143], v[190:193], v[56:59]
	v_mfma_f32_16x16x32_bf16 v[48:51], v[132:135], v[198:201], v[48:51]
	v_mfma_f32_16x16x32_bf16 v[44:47], v[140:143], v[198:201], v[44:47]
	v_mfma_f32_16x16x32_bf16 v[32:35], v[132:135], v[206:209], v[32:35]
	v_mfma_f32_16x16x32_bf16 v[28:31], v[140:143], v[206:209], v[28:31]
	v_mfma_f32_16x16x32_bf16 v[16:19], v[132:135], v[216:219], v[16:19]
	v_mfma_f32_16x16x32_bf16 v[12:15], v[140:143], v[216:219], v[12:15]
	v_mfma_f32_16x16x32_bf16 v[52:55], v[156:159], v[186:189], v[52:55]
	v_mfma_f32_16x16x32_bf16 v[40:43], v[170:173], v[186:189], v[40:43]
	v_mfma_f32_16x16x32_bf16 v[36:39], v[156:159], v[194:197], v[36:39]
	v_mfma_f32_16x16x32_bf16 v[24:27], v[170:173], v[194:197], v[24:27]
	v_mfma_f32_16x16x32_bf16 v[20:23], v[156:159], v[202:205], v[20:23]
	v_mfma_f32_16x16x32_bf16 v[8:11], v[170:173], v[202:205], v[8:11]
	v_mfma_f32_16x16x32_bf16 v[4:7], v[156:159], v[212:215], v[4:7]
	v_mfma_f32_16x16x32_bf16 v[0:3], v[170:173], v[212:215], v[0:3]
	v_mfma_f32_16x16x32_bf16 v[52:55], v[166:169], v[190:193], v[52:55]
	v_mfma_f32_16x16x32_bf16 v[40:43], v[182:185], v[190:193], v[40:43]
	v_mfma_f32_16x16x32_bf16 v[36:39], v[166:169], v[198:201], v[36:39]
	v_mfma_f32_16x16x32_bf16 v[24:27], v[182:185], v[198:201], v[24:27]
	v_mfma_f32_16x16x32_bf16 v[20:23], v[166:169], v[206:209], v[20:23]
	v_mfma_f32_16x16x32_bf16 v[8:11], v[182:185], v[206:209], v[8:11]
	v_mfma_f32_16x16x32_bf16 v[4:7], v[166:169], v[216:219], v[4:7]
	v_mfma_f32_16x16x32_bf16 v[0:3], v[182:185], v[216:219], v[0:3]
	s_barrier
	s_add_i32 s60, 0, 0x18000
	s_add_i32 s61, 0, 0x1c000
	v_add_u32_e32 v140, s60, v161
	v_add_u32_e32 v177, s61, v161
	ds_read_b128 v[128:131], v140
	ds_read_b128 v[132:135], v140 offset:1024
	ds_read_b128 v[136:139], v140 offset:2048
	ds_read_b128 v[140:143], v140 offset:3072
	ds_read_b128 v[156:159], v177
	ds_read_b128 v[166:169], v177 offset:1024
	ds_read_b128 v[170:173], v177 offset:2048
	ds_read_b128 v[182:185], v177 offset:3072
	s_add_u32 s20, s50, 0x40000
	s_addc_u32 s21, s51, 0
	s_mov_b32 m0, s67
	v_lshl_add_u64 v[226:227], s[20:21], 0, v[146:147]
	ds_read_b128 v[186:189], v165 offset:32768
	ds_read_b128 v[190:193], v165 offset:33792
	ds_read_b128 v[194:197], v165 offset:34816
	ds_read_b128 v[198:201], v165 offset:35840
	ds_read_b128 v[202:205], v165 offset:36864
	ds_read_b128 v[206:209], v165 offset:37888
	ds_read_b128 v[212:215], v165 offset:38912
	ds_read_b128 v[216:219], v165 offset:39936
	global_load_lds_dwordx4 v[226:227], off
	v_lshl_add_u64 v[226:227], s[20:21], 0, v[144:145]
	s_mov_b32 m0, s68
	s_nop 0
	global_load_lds_dwordx4 v[226:227], off
	s_waitcnt vmcnt(8)
	s_waitcnt lgkmcnt(0)
	s_barrier
	s_waitcnt lgkmcnt(0)
	v_mfma_f32_16x16x32_bf16 v[124:127], v[128:131], v[186:189], v[124:127]
	v_mfma_f32_16x16x32_bf16 v[120:123], v[136:139], v[186:189], v[120:123]
	v_mfma_f32_16x16x32_bf16 v[112:115], v[128:131], v[194:197], v[112:115]
	v_mfma_f32_16x16x32_bf16 v[108:111], v[136:139], v[194:197], v[108:111]
	v_mfma_f32_16x16x32_bf16 v[96:99], v[128:131], v[202:205], v[96:99]
	v_mfma_f32_16x16x32_bf16 v[92:95], v[136:139], v[202:205], v[92:95]
	v_mfma_f32_16x16x32_bf16 v[80:83], v[128:131], v[212:215], v[80:83]
	v_mfma_f32_16x16x32_bf16 v[76:79], v[136:139], v[212:215], v[76:79]
	v_mfma_f32_16x16x32_bf16 v[124:127], v[132:135], v[190:193], v[124:127]
	v_mfma_f32_16x16x32_bf16 v[120:123], v[140:143], v[190:193], v[120:123]
	v_mfma_f32_16x16x32_bf16 v[112:115], v[132:135], v[198:201], v[112:115]
	v_mfma_f32_16x16x32_bf16 v[108:111], v[140:143], v[198:201], v[108:111]
	v_mfma_f32_16x16x32_bf16 v[96:99], v[132:135], v[206:209], v[96:99]
	v_mfma_f32_16x16x32_bf16 v[92:95], v[140:143], v[206:209], v[92:95]
	v_mfma_f32_16x16x32_bf16 v[80:83], v[132:135], v[216:219], v[80:83]
	v_mfma_f32_16x16x32_bf16 v[76:79], v[140:143], v[216:219], v[76:79]
	v_mfma_f32_16x16x32_bf16 v[116:119], v[156:159], v[186:189], v[116:119]
	v_mfma_f32_16x16x32_bf16 v[104:107], v[170:173], v[186:189], v[104:107]
	v_mfma_f32_16x16x32_bf16 v[100:103], v[156:159], v[194:197], v[100:103]
	v_mfma_f32_16x16x32_bf16 v[88:91], v[170:173], v[194:197], v[88:91]
	v_mfma_f32_16x16x32_bf16 v[84:87], v[156:159], v[202:205], v[84:87]
	v_mfma_f32_16x16x32_bf16 v[72:75], v[170:173], v[202:205], v[72:75]
	v_mfma_f32_16x16x32_bf16 v[68:71], v[156:159], v[212:215], v[68:71]
	v_mfma_f32_16x16x32_bf16 v[64:67], v[170:173], v[212:215], v[64:67]
	v_mfma_f32_16x16x32_bf16 v[116:119], v[166:169], v[190:193], v[116:119]
	v_mfma_f32_16x16x32_bf16 v[104:107], v[182:185], v[190:193], v[104:107]
	v_mfma_f32_16x16x32_bf16 v[100:103], v[166:169], v[198:201], v[100:103]
	v_mfma_f32_16x16x32_bf16 v[88:91], v[182:185], v[198:201], v[88:91]
	v_mfma_f32_16x16x32_bf16 v[84:87], v[166:169], v[206:209], v[84:87]
	v_mfma_f32_16x16x32_bf16 v[72:75], v[182:185], v[206:209], v[72:75]
	v_mfma_f32_16x16x32_bf16 v[68:71], v[166:169], v[216:219], v[68:71]
	v_mfma_f32_16x16x32_bf16 v[64:67], v[182:185], v[216:219], v[64:67]
	s_barrier
; #define PG8_STAGE(bufoff, gbase, voff) do { _Pragma("unroll") for (int _i = 0; _i < 2; ++_i) \
;         __builtin_amdgcn_global_load_lds((const unsigned*)((const char*)(gbase) + (voff)[_i]), (PG8_LAS unsigned*)(lds + (bufoff) + ldsw + _i * 8192), 16, 0, 0); } while (0)
; #define PG8_LDA(dst, b, h) do { _Pragma("unroll") for (int m = 0; m < 4; ++m) _Pragma("unroll") for (int k = 0; k < 2; ++k) dst[m][k] = *(const PG8_LAS bf16x8*)(lds + PG8_SA(b, h) + aoff + m * 2048 + k * 1024); } while (0)
; #define PG8_MMA(ai, bj, At, Bt) do { __builtin_amdgcn_s_setprio(1); _Pragma("unroll") for (int m = 0; m < 4; ++m) _Pragma("unroll") for (int n = 0; n < 2; ++n) _Pragma("unroll") for (int k = 0; k < 2; ++k) \
;         acc[ai][bj][m][n] = __builtin_amdgcn_mfma_f32_16x16x32_bf16(Bt[n][k], At[m][k], acc[ai][bj][m][n], 0, 0, 0); __builtin_amdgcn_s_setprio(0); } while (0)
; #define PG8_WAIT_V(n) asm volatile("s_waitcnt vmcnt(" #n ")" ::: "memory")
; #define PG8_WAIT_L(n) asm volatile("s_waitcnt lgkmcnt(" #n ")" ::: "memory")
; #define PG8_BAR __builtin_amdgcn_s_barrier()
; #define PG8_SCHED __builtin_amdgcn_sched_barrier(0)
; template <class Epi, class Sched, bool ALIGN_EPI = false, bool SP2 = false>
; __device__ __forceinline__ void gemm_phase(PG8_LAS unsigned char* lds, const Gemm g, const Sched& S, const Epi& E) {
;     ...
;             PG8_LDA(At, 1, 1); PG8_STAGE(PG8_SB(1, 0), b3, voffB); PG8_STAGE(PG8_SB(1, 1), b3 + hstep, voffB); PG8_STAGE(PG8_SA(1, 0), a3, voffA);
;             PG8_WAIT_V(8); PG8_WAIT_L(0); PG8_BAR; PG8_MMA(1, 0, At, B0); PG8_MMA(1, 1, At, B1); PG8_BAR; PG8_SCHED;
	s_add_i32 s20, s60, s3
	v_lshl_add_u64 v[174:175], v[174:175], 0, s[10:11]
	s_mov_b32 m0, s20
	ds_read_b128 v[186:189], v165 offset:49152
	ds_read_b128 v[190:193], v165 offset:50176
	ds_read_b128 v[194:197], v165 offset:51200
	ds_read_b128 v[198:201], v165 offset:52224
	ds_read_b128 v[202:205], v165 offset:53248
	ds_read_b128 v[206:209], v165 offset:54272
	ds_read_b128 v[212:215], v165 offset:55296
	ds_read_b128 v[216:219], v165 offset:56320
	global_load_lds_dwordx4 v[174:175], off
	s_add_i32 m0, s20, 0x2000
	s_add_u32 s20, s48, 0x40080
	v_lshl_add_u64 v[174:175], v[220:221], 0, s[10:11]
	s_addc_u32 s21, s49, 0
	s_add_i32 s48, s61, s3
	global_load_lds_dwordx4 v[174:175], off
	v_lshl_add_u64 v[174:175], s[20:21], 0, v[146:147]
	s_mov_b32 m0, s48
	s_nop 0
	global_load_lds_dwordx4 v[174:175], off
	v_lshl_add_u64 v[174:175], s[20:21], 0, v[144:145]
	s_add_i32 m0, s48, 0x2000
	s_nop 0
	global_load_lds_dwordx4 v[174:175], off
	v_lshl_add_u64 v[174:175], v[222:223], 0, s[10:11]
	s_mov_b32 m0, s71
	s_nop 0
	global_load_lds_dwordx4 v[174:175], off
	v_lshl_add_u64 v[174:175], v[224:225], 0, s[10:11]
	s_mov_b32 m0, s72
	s_nop 0
	global_load_lds_dwordx4 v[174:175], off
	s_waitcnt vmcnt(8)
	s_waitcnt lgkmcnt(0)
	s_barrier
	s_waitcnt lgkmcnt(0)
	v_mfma_f32_16x16x32_bf16 v[60:63], v[128:131], v[186:189], v[60:63]
	v_mfma_f32_16x16x32_bf16 v[56:59], v[136:139], v[186:189], v[56:59]
	v_mfma_f32_16x16x32_bf16 v[48:51], v[128:131], v[194:197], v[48:51]
	v_mfma_f32_16x16x32_bf16 v[44:47], v[136:139], v[194:197], v[44:47]
	v_mfma_f32_16x16x32_bf16 v[32:35], v[128:131], v[202:205], v[32:35]
	v_mfma_f32_16x16x32_bf16 v[28:31], v[136:139], v[202:205], v[28:31]
	v_mfma_f32_16x16x32_bf16 v[16:19], v[128:131], v[212:215], v[16:19]
	v_mfma_f32_16x16x32_bf16 v[12:15], v[136:139], v[212:215], v[12:15]
	v_mfma_f32_16x16x32_bf16 v[60:63], v[132:135], v[190:193], v[60:63]
	v_mfma_f32_16x16x32_bf16 v[56:59], v[140:143], v[190:193], v[56:59]
	v_mfma_f32_16x16x32_bf16 v[48:51], v[132:135], v[198:201], v[48:51]
	v_mfma_f32_16x16x32_bf16 v[44:47], v[140:143], v[198:201], v[44:47]
	v_mfma_f32_16x16x32_bf16 v[32:35], v[132:135], v[206:209], v[32:35]
	v_mfma_f32_16x16x32_bf16 v[28:31], v[140:143], v[206:209], v[28:31]
	v_mfma_f32_16x16x32_bf16 v[16:19], v[132:135], v[216:219], v[16:19]
	v_mfma_f32_16x16x32_bf16 v[12:15], v[140:143], v[216:219], v[12:15]
	v_mfma_f32_16x16x32_bf16 v[52:55], v[156:159], v[186:189], v[52:55]
	v_mfma_f32_16x16x32_bf16 v[40:43], v[170:173], v[186:189], v[40:43]
	v_mfma_f32_16x16x32_bf16 v[36:39], v[156:159], v[194:197], v[36:39]
	v_mfma_f32_16x16x32_bf16 v[24:27], v[170:173], v[194:197], v[24:27]
	v_mfma_f32_16x16x32_bf16 v[20:23], v[156:159], v[202:205], v[20:23]
	v_mfma_f32_16x16x32_bf16 v[8:11], v[170:173], v[202:205], v[8:11]
	v_mfma_f32_16x16x32_bf16 v[4:7], v[156:159], v[212:215], v[4:7]
	v_mfma_f32_16x16x32_bf16 v[0:3], v[170:173], v[212:215], v[0:3]
	v_mfma_f32_16x16x32_bf16 v[52:55], v[166:169], v[190:193], v[52:55]
	v_mfma_f32_16x16x32_bf16 v[40:43], v[182:185], v[190:193], v[40:43]
	v_mfma_f32_16x16x32_bf16 v[36:39], v[166:169], v[198:201], v[36:39]
	v_mfma_f32_16x16x32_bf16 v[24:27], v[182:185], v[198:201], v[24:27]
	v_mfma_f32_16x16x32_bf16 v[20:23], v[166:169], v[206:209], v[20:23]
	v_mfma_f32_16x16x32_bf16 v[8:11], v[182:185], v[206:209], v[8:11]
	v_mfma_f32_16x16x32_bf16 v[4:7], v[166:169], v[216:219], v[4:7]
	v_mfma_f32_16x16x32_bf16 v[0:3], v[182:185], v[216:219], v[0:3]
	s_barrier
	s_add_i32 s79, s79, 2
	s_add_u32 s46, s46, 0x100
	s_addc_u32 s47, s47, 0
	s_add_u32 s45, s45, 0x100
	s_addc_u32 s78, s78, 0
	s_cmp_gt_u32 s79, 13
	s_cbranch_scc0 .LBB0_543
	s_and_b64 vcc, exec, s[28:29]
	s_cbranch_vccz .LBB0_546
	s_barrier

; #define PG8_STAGE(bufoff, gbase, voff) do { _Pragma("unroll") for (int _i = 0; _i < 2; ++_i) \
;         __builtin_amdgcn_global_load_lds((const unsigned*)((const char*)(gbase) + (voff)[_i]), (PG8_LAS unsigned*)(lds + (bufoff) + ldsw + _i * 8192), 16, 0, 0); } while (0)
; #define PG8_LDA(dst, b, h) do { _Pragma("unroll") for (int m = 0; m < 4; ++m) _Pragma("unroll") for (int k = 0; k < 2; ++k) dst[m][k] = *(const PG8_LAS bf16x8*)(lds + PG8_SA(b, h) + aoff + m * 2048 + k * 1024); } while (0)
; #define PG8_LDB(dst, b, h) do { _Pragma("unroll") for (int n = 0; n < 2; ++n) _Pragma("unroll") for (int k = 0; k < 2; ++k) dst[n][k] = *(const PG8_LAS bf16x8*)(lds + PG8_SB(b, h) + boff + n * 2048 + k * 1024); } while (0)
; #define PG8_MMA(ai, bj, At, Bt) do { __builtin_amdgcn_s_setprio(1); _Pragma("unroll") for (int m = 0; m < 4; ++m) _Pragma("unroll") for (int n = 0; n < 2; ++n) _Pragma("unroll") for (int k = 0; k < 2; ++k) \
;         acc[ai][bj][m][n] = __builtin_amdgcn_mfma_f32_16x16x32_bf16(Bt[n][k], At[m][k], acc[ai][bj][m][n], 0, 0, 0); __builtin_amdgcn_s_setprio(0); } while (0)
; #define PG8_WAIT_V(n) asm volatile("s_waitcnt vmcnt(" #n ")" ::: "memory")
; #define PG8_BAR __builtin_amdgcn_s_barrier()
; template <class Epi, class Sched, bool ALIGN_EPI = false, bool SP2 = false>
; __device__ __forceinline__ void gemm_phase(PG8_LAS unsigned char* lds, const Gemm g, const Sched& S, const Epi& E) {
;     ...
;         for (int t = 0; t < nt_u; t += 2) {
;             const bool last = (t == nt_u - 2);
;             const char* a1 = cA + (size_t)(t + 1) * kstep;
;             const char* a2 = last ? nA : cA + (size_t)(t + 2) * kstep; const char* b2 = last ? nB : cB + (size_t)(t + 2) * kstep;
;             const char* a3 = a2 + kstep; const char* b3 = b2 + kstep;
;             if (last && has_next) S.a_ready(nxt);
;             if constexpr (SP2) {
;             PG8_LDB(B0, 0, 0); PG8_LDB(B1, 0, 1); PG8_SCHED; PG8_LDA(At, 0, 0); PG8_STAGE(PG8_SA(1, 1), a1 + hstep, voffA);
;             PG8_WAIT_V(8); PG8_WAIT_L(0); PG8_BAR; PG8_MMA(0, 0, At, B0); PG8_MMA(0, 1, At, B1); PG8_BAR; PG8_SCHED;
;             PG8_LDA(At, 0, 1); PG8_STAGE(PG8_SB(0, 0), b2, voffB); PG8_STAGE(PG8_SB(0, 1), b2 + hstep, voffB); PG8_STAGE(PG8_SA(0, 0), a2, voffA);
;             PG8_WAIT_V(8); PG8_WAIT_L(0); PG8_BAR; PG8_MMA(1, 0, At, B0); PG8_MMA(1, 1, At, B1); PG8_BAR; PG8_SCHED;
.LBB0_668:
	ds_read_b128 v[128:131], v207
	ds_read_b128 v[132:135], v207 offset:1024
	ds_read_b128 v[136:139], v207 offset:2048
	ds_read_b128 v[140:143], v207 offset:3072
	ds_read_b128 v[144:147], v208
	ds_read_b128 v[148:151], v208 offset:1024
	ds_read_b128 v[152:155], v208 offset:2048
	ds_read_b128 v[156:159], v208 offset:3072
	s_add_u32 s16, s0, 0xfffc0080
	s_addc_u32 s17, s1, -1
	s_cmp_eq_u32 s83, 12
	s_cselect_b32 s63, s12, s17
	s_cselect_b32 s62, s13, s16
	s_cselect_b32 s17, s45, s82
	s_cselect_b32 s16, s47, s81
	v_lshl_add_u64 v[196:197], s[0:1], 0, v[168:169]
	s_add_i32 m0, s66, 0xc000
	ds_read_b128 v[180:183], v209
	ds_read_b128 v[184:187], v209 offset:1024
	ds_read_b128 v[188:191], v209 offset:2048
	ds_read_b128 v[192:195], v209 offset:3072
	ds_read_b128 v[212:215], v209 offset:4096
	ds_read_b128 v[216:219], v209 offset:5120
	ds_read_b128 v[220:223], v209 offset:6144
	ds_read_b128 v[224:227], v209 offset:7168
	global_load_lds_dwordx4 v[196:197], off
	v_lshl_add_u64 v[196:197], s[0:1], 0, v[170:171]
	s_add_i32 m0, s66, 0xe000
	s_nop 0
	global_load_lds_dwordx4 v[196:197], off
	s_waitcnt vmcnt(8)
	s_waitcnt lgkmcnt(0)
	s_barrier
	s_waitcnt lgkmcnt(0)
	v_mfma_f32_16x16x32_bf16 v[124:127], v[128:131], v[180:183], v[124:127]
	v_mfma_f32_16x16x32_bf16 v[60:63], v[136:139], v[180:183], v[60:63]
	v_mfma_f32_16x16x32_bf16 v[116:119], v[128:131], v[188:191], v[116:119]
	v_mfma_f32_16x16x32_bf16 v[52:55], v[136:139], v[188:191], v[52:55]
	v_mfma_f32_16x16x32_bf16 v[108:111], v[128:131], v[212:215], v[108:111]
	v_mfma_f32_16x16x32_bf16 v[44:47], v[136:139], v[212:215], v[44:47]
	v_mfma_f32_16x16x32_bf16 v[104:107], v[128:131], v[220:223], v[104:107]
	v_mfma_f32_16x16x32_bf16 v[40:43], v[136:139], v[220:223], v[40:43]
	v_mfma_f32_16x16x32_bf16 v[124:127], v[132:135], v[184:187], v[124:127]
	v_mfma_f32_16x16x32_bf16 v[60:63], v[140:143], v[184:187], v[60:63]
	v_mfma_f32_16x16x32_bf16 v[116:119], v[132:135], v[192:195], v[116:119]
	v_mfma_f32_16x16x32_bf16 v[52:55], v[140:143], v[192:195], v[52:55]
	v_mfma_f32_16x16x32_bf16 v[108:111], v[132:135], v[216:219], v[108:111]
	v_mfma_f32_16x16x32_bf16 v[44:47], v[140:143], v[216:219], v[44:47]
	v_mfma_f32_16x16x32_bf16 v[104:107], v[132:135], v[224:227], v[104:107]
	v_mfma_f32_16x16x32_bf16 v[40:43], v[140:143], v[224:227], v[40:43]
	v_mfma_f32_16x16x32_bf16 v[120:123], v[144:147], v[180:183], v[120:123]
	v_mfma_f32_16x16x32_bf16 v[56:59], v[152:155], v[180:183], v[56:59]
	v_mfma_f32_16x16x32_bf16 v[112:115], v[144:147], v[188:191], v[112:115]
	v_mfma_f32_16x16x32_bf16 v[48:51], v[152:155], v[188:191], v[48:51]
	v_mfma_f32_16x16x32_bf16 v[100:103], v[144:147], v[212:215], v[100:103]
	v_mfma_f32_16x16x32_bf16 v[36:39], v[152:155], v[212:215], v[36:39]
	v_mfma_f32_16x16x32_bf16 v[96:99], v[144:147], v[220:223], v[96:99]
	v_mfma_f32_16x16x32_bf16 v[32:35], v[152:155], v[220:223], v[32:35]
	v_mfma_f32_16x16x32_bf16 v[120:123], v[148:151], v[184:187], v[120:123]
	v_mfma_f32_16x16x32_bf16 v[56:59], v[156:159], v[184:187], v[56:59]
	v_mfma_f32_16x16x32_bf16 v[112:115], v[148:151], v[192:195], v[112:115]
	v_mfma_f32_16x16x32_bf16 v[48:51], v[156:159], v[192:195], v[48:51]
	v_mfma_f32_16x16x32_bf16 v[100:103], v[148:151], v[216:219], v[100:103]
	v_mfma_f32_16x16x32_bf16 v[36:39], v[156:159], v[216:219], v[36:39]
	v_mfma_f32_16x16x32_bf16 v[96:99], v[148:151], v[224:227], v[96:99]
	v_mfma_f32_16x16x32_bf16 v[32:35], v[156:159], v[224:227], v[32:35]
	s_barrier
	s_add_i32 s20, s77, s3
	v_lshl_add_u64 v[196:197], s[16:17], 0, v[162:163]
	s_mov_b32 m0, s20
	ds_read_b128 v[180:183], v209 offset:16384
	ds_read_b128 v[184:187], v209 offset:17408
	ds_read_b128 v[188:191], v209 offset:18432
	ds_read_b128 v[192:195], v209 offset:19456
	ds_read_b128 v[212:215], v209 offset:20480
	ds_read_b128 v[216:219], v209 offset:21504
	ds_read_b128 v[220:223], v209 offset:22528
	ds_read_b128 v[224:227], v209 offset:23552
	global_load_lds_dwordx4 v[196:197], off
	s_add_i32 m0, s20, 0x2000
	s_add_u32 s20, s16, 0x40000
	v_lshl_add_u64 v[228:229], s[16:17], 0, v[160:161]
	s_addc_u32 s21, s17, 0
	s_add_i32 s64, s78, s3
	global_load_lds_dwordx4 v[228:229], off
	v_lshl_add_u64 v[230:231], s[20:21], 0, v[162:163]
	s_mov_b32 m0, s64
	v_lshl_add_u64 v[232:233], s[62:63], 0, v[160:161]
	global_load_lds_dwordx4 v[230:231], off
	v_lshl_add_u64 v[230:231], s[20:21], 0, v[160:161]
	s_add_i32 m0, s64, 0x2000
	s_nop 0
	global_load_lds_dwordx4 v[230:231], off
	v_lshl_add_u64 v[230:231], s[62:63], 0, v[162:163]
	s_mov_b32 m0, s66
	s_nop 0
	global_load_lds_dwordx4 v[230:231], off
	s_mov_b32 m0, s67
	s_nop 0
	global_load_lds_dwordx4 v[232:233], off
	s_waitcnt vmcnt(8)
	s_waitcnt lgkmcnt(0)
	s_barrier
; #define PG8_STAGE(bufoff, gbase, voff) do { _Pragma("unroll") for (int _i = 0; _i < 2; ++_i) \
;         __builtin_amdgcn_global_load_lds((const unsigned*)((const char*)(gbase) + (voff)[_i]), (PG8_LAS unsigned*)(lds + (bufoff) + ldsw + _i * 8192), 16, 0, 0); } while (0)
; #define PG8_LDA(dst, b, h) do { _Pragma("unroll") for (int m = 0; m < 4; ++m) _Pragma("unroll") for (int k = 0; k < 2; ++k) dst[m][k] = *(const PG8_LAS bf16x8*)(lds + PG8_SA(b, h) + aoff + m * 2048 + k * 1024); } while (0)
; #define PG8_LDB(dst, b, h) do { _Pragma("unroll") for (int n = 0; n < 2; ++n) _Pragma("unroll") for (int k = 0; k < 2; ++k) dst[n][k] = *(const PG8_LAS bf16x8*)(lds + PG8_SB(b, h) + boff + n * 2048 + k * 1024); } while (0)
; #define PG8_MMA(ai, bj, At, Bt) do { __builtin_amdgcn_s_setprio(1); _Pragma("unroll") for (int m = 0; m < 4; ++m) _Pragma("unroll") for (int n = 0; n < 2; ++n) _Pragma("unroll") for (int k = 0; k < 2; ++k) \
;         acc[ai][bj][m][n] = __builtin_amdgcn_mfma_f32_16x16x32_bf16(Bt[n][k], At[m][k], acc[ai][bj][m][n], 0, 0, 0); __builtin_amdgcn_s_setprio(0); } while (0)
; #define PG8_WAIT_V(n) asm volatile("s_waitcnt vmcnt(" #n ")" ::: "memory")
; #define PG8_WAIT_L(n) asm volatile("s_waitcnt lgkmcnt(" #n ")" ::: "memory")
; #define PG8_BAR __builtin_amdgcn_s_barrier()
; #define PG8_SCHED __builtin_amdgcn_sched_barrier(0)
; template <class Epi, class Sched, bool ALIGN_EPI = false, bool SP2 = false>
; __device__ __forceinline__ void gemm_phase(PG8_LAS unsigned char* lds, const Gemm g, const Sched& S, const Epi& E) {
;     ...
;             PG8_WAIT_V(8); PG8_WAIT_L(0); PG8_BAR; PG8_MMA(1, 0, At, B0); PG8_MMA(1, 1, At, B1); PG8_BAR; PG8_SCHED;
;             PG8_LDB(B0, 1, 0); PG8_LDB(B1, 1, 1); PG8_SCHED; PG8_LDA(At, 1, 0); PG8_STAGE(PG8_SA(0, 1), a2 + hstep, voffA);
;             PG8_WAIT_V(8); PG8_WAIT_L(0); PG8_BAR; PG8_MMA(0, 0, At, B0); PG8_MMA(0, 1, At, B1); PG8_BAR; PG8_SCHED;
	s_waitcnt lgkmcnt(0)
	v_mfma_f32_16x16x32_bf16 v[92:95], v[128:131], v[180:183], v[92:95]
	v_mfma_f32_16x16x32_bf16 v[28:31], v[136:139], v[180:183], v[28:31]
	v_mfma_f32_16x16x32_bf16 v[84:87], v[128:131], v[188:191], v[84:87]
	v_mfma_f32_16x16x32_bf16 v[20:23], v[136:139], v[188:191], v[20:23]
	v_mfma_f32_16x16x32_bf16 v[76:79], v[128:131], v[212:215], v[76:79]
	v_mfma_f32_16x16x32_bf16 v[12:15], v[136:139], v[212:215], v[12:15]
	v_mfma_f32_16x16x32_bf16 v[72:75], v[128:131], v[220:223], v[72:75]
	v_mfma_f32_16x16x32_bf16 v[8:11], v[136:139], v[220:223], v[8:11]
	v_mfma_f32_16x16x32_bf16 v[92:95], v[132:135], v[184:187], v[92:95]
	v_mfma_f32_16x16x32_bf16 v[28:31], v[140:143], v[184:187], v[28:31]
	v_mfma_f32_16x16x32_bf16 v[84:87], v[132:135], v[192:195], v[84:87]
	v_mfma_f32_16x16x32_bf16 v[20:23], v[140:143], v[192:195], v[20:23]
	v_mfma_f32_16x16x32_bf16 v[76:79], v[132:135], v[216:219], v[76:79]
	v_mfma_f32_16x16x32_bf16 v[12:15], v[140:143], v[216:219], v[12:15]
	v_mfma_f32_16x16x32_bf16 v[72:75], v[132:135], v[224:227], v[72:75]
	v_mfma_f32_16x16x32_bf16 v[8:11], v[140:143], v[224:227], v[8:11]
	v_mfma_f32_16x16x32_bf16 v[88:91], v[144:147], v[180:183], v[88:91]
	v_mfma_f32_16x16x32_bf16 v[24:27], v[152:155], v[180:183], v[24:27]
	v_mfma_f32_16x16x32_bf16 v[80:83], v[144:147], v[188:191], v[80:83]
	v_mfma_f32_16x16x32_bf16 v[16:19], v[152:155], v[188:191], v[16:19]
	v_mfma_f32_16x16x32_bf16 v[68:71], v[144:147], v[212:215], v[68:71]
	v_mfma_f32_16x16x32_bf16 v[4:7], v[152:155], v[212:215], v[4:7]
	v_mfma_f32_16x16x32_bf16 v[64:67], v[144:147], v[220:223], v[64:67]
	v_mfma_f32_16x16x32_bf16 v[0:3], v[152:155], v[220:223], v[0:3]
	v_mfma_f32_16x16x32_bf16 v[88:91], v[148:151], v[184:187], v[88:91]
	v_mfma_f32_16x16x32_bf16 v[24:27], v[156:159], v[184:187], v[24:27]
	v_mfma_f32_16x16x32_bf16 v[80:83], v[148:151], v[192:195], v[80:83]
	v_mfma_f32_16x16x32_bf16 v[16:19], v[156:159], v[192:195], v[16:19]
	v_mfma_f32_16x16x32_bf16 v[68:71], v[148:151], v[216:219], v[68:71]
	v_mfma_f32_16x16x32_bf16 v[4:7], v[156:159], v[216:219], v[4:7]
	v_mfma_f32_16x16x32_bf16 v[64:67], v[148:151], v[224:227], v[64:67]
	v_mfma_f32_16x16x32_bf16 v[0:3], v[156:159], v[224:227], v[0:3]
	s_barrier
	s_add_i32 s64, 0, 0x18000
	s_add_i32 s65, 0, 0x1c000
	v_add_u32_e32 v140, s64, v177
	v_add_u32_e32 v156, s65, v177
	ds_read_b128 v[128:131], v140
	ds_read_b128 v[132:135], v140 offset:1024
	ds_read_b128 v[136:139], v140 offset:2048
	ds_read_b128 v[140:143], v140 offset:3072
	ds_read_b128 v[144:147], v156
	ds_read_b128 v[148:151], v156 offset:1024
	ds_read_b128 v[152:155], v156 offset:2048
	ds_read_b128 v[156:159], v156 offset:3072
	s_add_u32 s20, s62, 0x40000
	s_addc_u32 s21, s63, 0
	s_mov_b32 m0, s68
	v_lshl_add_u64 v[234:235], s[20:21], 0, v[162:163]
	ds_read_b128 v[180:183], v209 offset:32768
	ds_read_b128 v[184:187], v209 offset:33792
	ds_read_b128 v[188:191], v209 offset:34816
	ds_read_b128 v[192:195], v209 offset:35840
	ds_read_b128 v[212:215], v209 offset:36864
	ds_read_b128 v[216:219], v209 offset:37888
	ds_read_b128 v[220:223], v209 offset:38912
	ds_read_b128 v[224:227], v209 offset:39936
	global_load_lds_dwordx4 v[234:235], off
	v_lshl_add_u64 v[234:235], s[20:21], 0, v[160:161]
	s_mov_b32 m0, s69
	s_nop 0
	global_load_lds_dwordx4 v[234:235], off
	s_waitcnt vmcnt(8)
	s_waitcnt lgkmcnt(0)
	s_barrier
	s_waitcnt lgkmcnt(0)
	v_mfma_f32_16x16x32_bf16 v[124:127], v[128:131], v[180:183], v[124:127]
	v_mfma_f32_16x16x32_bf16 v[60:63], v[136:139], v[180:183], v[60:63]
	v_mfma_f32_16x16x32_bf16 v[116:119], v[128:131], v[188:191], v[116:119]
	v_mfma_f32_16x16x32_bf16 v[52:55], v[136:139], v[188:191], v[52:55]
	v_mfma_f32_16x16x32_bf16 v[108:111], v[128:131], v[212:215], v[108:111]
	v_mfma_f32_16x16x32_bf16 v[44:47], v[136:139], v[212:215], v[44:47]
	v_mfma_f32_16x16x32_bf16 v[104:107], v[128:131], v[220:223], v[104:107]
	v_mfma_f32_16x16x32_bf16 v[40:43], v[136:139], v[220:223], v[40:43]
	v_mfma_f32_16x16x32_bf16 v[124:127], v[132:135], v[184:187], v[124:127]
	v_mfma_f32_16x16x32_bf16 v[60:63], v[140:143], v[184:187], v[60:63]
	v_mfma_f32_16x16x32_bf16 v[116:119], v[132:135], v[192:195], v[116:119]
	v_mfma_f32_16x16x32_bf16 v[52:55], v[140:143], v[192:195], v[52:55]
	v_mfma_f32_16x16x32_bf16 v[108:111], v[132:135], v[216:219], v[108:111]
	v_mfma_f32_16x16x32_bf16 v[44:47], v[140:143], v[216:219], v[44:47]
	v_mfma_f32_16x16x32_bf16 v[104:107], v[132:135], v[224:227], v[104:107]
	v_mfma_f32_16x16x32_bf16 v[40:43], v[140:143], v[224:227], v[40:43]
	v_mfma_f32_16x16x32_bf16 v[120:123], v[144:147], v[180:183], v[120:123]
	v_mfma_f32_16x16x32_bf16 v[56:59], v[152:155], v[180:183], v[56:59]
	v_mfma_f32_16x16x32_bf16 v[112:115], v[144:147], v[188:191], v[112:115]
	v_mfma_f32_16x16x32_bf16 v[48:51], v[152:155], v[188:191], v[48:51]
	v_mfma_f32_16x16x32_bf16 v[100:103], v[144:147], v[212:215], v[100:103]
	v_mfma_f32_16x16x32_bf16 v[36:39], v[152:155], v[212:215], v[36:39]
	v_mfma_f32_16x16x32_bf16 v[96:99], v[144:147], v[220:223], v[96:99]
	v_mfma_f32_16x16x32_bf16 v[32:35], v[152:155], v[220:223], v[32:35]
	v_mfma_f32_16x16x32_bf16 v[120:123], v[148:151], v[184:187], v[120:123]
	v_mfma_f32_16x16x32_bf16 v[56:59], v[156:159], v[184:187], v[56:59]
	v_mfma_f32_16x16x32_bf16 v[112:115], v[148:151], v[192:195], v[112:115]
	v_mfma_f32_16x16x32_bf16 v[48:51], v[156:159], v[192:195], v[48:51]
	v_mfma_f32_16x16x32_bf16 v[100:103], v[148:151], v[216:219], v[100:103]
	v_mfma_f32_16x16x32_bf16 v[36:39], v[156:159], v[216:219], v[36:39]
	v_mfma_f32_16x16x32_bf16 v[96:99], v[148:151], v[224:227], v[96:99]
	v_mfma_f32_16x16x32_bf16 v[32:35], v[156:159], v[224:227], v[32:35]
	s_barrier
; #define PG8_STAGE(bufoff, gbase, voff) do { _Pragma("unroll") for (int _i = 0; _i < 2; ++_i) \
;         __builtin_amdgcn_global_load_lds((const unsigned*)((const char*)(gbase) + (voff)[_i]), (PG8_LAS unsigned*)(lds + (bufoff) + ldsw + _i * 8192), 16, 0, 0); } while (0)
; #define PG8_LDA(dst, b, h) do { _Pragma("unroll") for (int m = 0; m < 4; ++m) _Pragma("unroll") for (int k = 0; k < 2; ++k) dst[m][k] = *(const PG8_LAS bf16x8*)(lds + PG8_SA(b, h) + aoff + m * 2048 + k * 1024); } while (0)
; #define PG8_MMA(ai, bj, At, Bt) do { __builtin_amdgcn_s_setprio(1); _Pragma("unroll") for (int m = 0; m < 4; ++m) _Pragma("unroll") for (int n = 0; n < 2; ++n) _Pragma("unroll") for (int k = 0; k < 2; ++k) \
;         acc[ai][bj][m][n] = __builtin_amdgcn_mfma_f32_16x16x32_bf16(Bt[n][k], At[m][k], acc[ai][bj][m][n], 0, 0, 0); __builtin_amdgcn_s_setprio(0); } while (0)
; #define PG8_WAIT_V(n) asm volatile("s_waitcnt vmcnt(" #n ")" ::: "memory")
; #define PG8_WAIT_L(n) asm volatile("s_waitcnt lgkmcnt(" #n ")" ::: "memory")
; #define PG8_BAR __builtin_amdgcn_s_barrier()
; #define PG8_SCHED __builtin_amdgcn_sched_barrier(0)
; template <class Epi, class Sched, bool ALIGN_EPI = false, bool SP2 = false>
; __device__ __forceinline__ void gemm_phase(PG8_LAS unsigned char* lds, const Gemm g, const Sched& S, const Epi& E) {
;     ...
;             PG8_LDA(At, 1, 1); PG8_STAGE(PG8_SB(1, 0), b3, voffB); PG8_STAGE(PG8_SB(1, 1), b3 + hstep, voffB); PG8_STAGE(PG8_SA(1, 0), a3, voffA);
;             PG8_WAIT_V(8); PG8_WAIT_L(0); PG8_BAR; PG8_MMA(1, 0, At, B0); PG8_MMA(1, 1, At, B1); PG8_BAR; PG8_SCHED;
;     ...
;         if constexpr (ALIGN_EPI) { if (wr == 0) PG8_BAR; }
	s_add_i32 s20, s64, s3
	v_lshl_add_u64 v[196:197], v[196:197], 0, s[30:31]
	s_mov_b32 m0, s20
	ds_read_b128 v[180:183], v209 offset:49152
	ds_read_b128 v[184:187], v209 offset:50176
	ds_read_b128 v[188:191], v209 offset:51200
	ds_read_b128 v[192:195], v209 offset:52224
	ds_read_b128 v[212:215], v209 offset:53248
	ds_read_b128 v[216:219], v209 offset:54272
	ds_read_b128 v[220:223], v209 offset:55296
	ds_read_b128 v[224:227], v209 offset:56320
	global_load_lds_dwordx4 v[196:197], off
	s_add_i32 m0, s20, 0x2000
	s_add_u32 s16, s16, 0x40080
	v_lshl_add_u64 v[196:197], v[228:229], 0, s[30:31]
	s_addc_u32 s17, s17, 0
	s_add_i32 s20, s65, s3
	global_load_lds_dwordx4 v[196:197], off
	v_lshl_add_u64 v[196:197], s[16:17], 0, v[162:163]
	s_mov_b32 m0, s20
	s_nop 0
	global_load_lds_dwordx4 v[196:197], off
	v_lshl_add_u64 v[196:197], s[16:17], 0, v[160:161]
	s_add_i32 m0, s20, 0x2000
	s_nop 0
	global_load_lds_dwordx4 v[196:197], off
	v_lshl_add_u64 v[196:197], v[230:231], 0, s[30:31]
	s_mov_b32 m0, s71
	s_nop 0
	global_load_lds_dwordx4 v[196:197], off
	v_lshl_add_u64 v[196:197], v[232:233], 0, s[30:31]
	s_mov_b32 m0, s72
	s_nop 0
	global_load_lds_dwordx4 v[196:197], off
	s_waitcnt vmcnt(8)
	s_waitcnt lgkmcnt(0)
	s_barrier
	s_waitcnt lgkmcnt(0)
	v_mfma_f32_16x16x32_bf16 v[92:95], v[128:131], v[180:183], v[92:95]
	v_mfma_f32_16x16x32_bf16 v[28:31], v[136:139], v[180:183], v[28:31]
	v_mfma_f32_16x16x32_bf16 v[84:87], v[128:131], v[188:191], v[84:87]
	v_mfma_f32_16x16x32_bf16 v[20:23], v[136:139], v[188:191], v[20:23]
	v_mfma_f32_16x16x32_bf16 v[76:79], v[128:131], v[212:215], v[76:79]
	v_mfma_f32_16x16x32_bf16 v[12:15], v[136:139], v[212:215], v[12:15]
	v_mfma_f32_16x16x32_bf16 v[72:75], v[128:131], v[220:223], v[72:75]
	v_mfma_f32_16x16x32_bf16 v[8:11], v[136:139], v[220:223], v[8:11]
	v_mfma_f32_16x16x32_bf16 v[92:95], v[132:135], v[184:187], v[92:95]
	v_mfma_f32_16x16x32_bf16 v[28:31], v[140:143], v[184:187], v[28:31]
	v_mfma_f32_16x16x32_bf16 v[84:87], v[132:135], v[192:195], v[84:87]
	v_mfma_f32_16x16x32_bf16 v[20:23], v[140:143], v[192:195], v[20:23]
	v_mfma_f32_16x16x32_bf16 v[76:79], v[132:135], v[216:219], v[76:79]
	v_mfma_f32_16x16x32_bf16 v[12:15], v[140:143], v[216:219], v[12:15]
	v_mfma_f32_16x16x32_bf16 v[72:75], v[132:135], v[224:227], v[72:75]
	v_mfma_f32_16x16x32_bf16 v[8:11], v[140:143], v[224:227], v[8:11]
	v_mfma_f32_16x16x32_bf16 v[88:91], v[144:147], v[180:183], v[88:91]
	v_mfma_f32_16x16x32_bf16 v[24:27], v[152:155], v[180:183], v[24:27]
	v_mfma_f32_16x16x32_bf16 v[80:83], v[144:147], v[188:191], v[80:83]
	v_mfma_f32_16x16x32_bf16 v[16:19], v[152:155], v[188:191], v[16:19]
	v_mfma_f32_16x16x32_bf16 v[68:71], v[144:147], v[212:215], v[68:71]
	v_mfma_f32_16x16x32_bf16 v[4:7], v[152:155], v[212:215], v[4:7]
	v_mfma_f32_16x16x32_bf16 v[64:67], v[144:147], v[220:223], v[64:67]
	v_mfma_f32_16x16x32_bf16 v[0:3], v[152:155], v[220:223], v[0:3]
	v_mfma_f32_16x16x32_bf16 v[88:91], v[148:151], v[184:187], v[88:91]
	v_mfma_f32_16x16x32_bf16 v[24:27], v[156:159], v[184:187], v[24:27]
	v_mfma_f32_16x16x32_bf16 v[80:83], v[148:151], v[192:195], v[80:83]
	v_mfma_f32_16x16x32_bf16 v[16:19], v[156:159], v[192:195], v[16:19]
	v_mfma_f32_16x16x32_bf16 v[68:71], v[148:151], v[216:219], v[68:71]
	v_mfma_f32_16x16x32_bf16 v[4:7], v[156:159], v[216:219], v[4:7]
	v_mfma_f32_16x16x32_bf16 v[64:67], v[148:151], v[224:227], v[64:67]
	v_mfma_f32_16x16x32_bf16 v[0:3], v[156:159], v[224:227], v[0:3]
	s_barrier
	s_add_i32 s83, s83, 2
	s_add_u32 s0, s0, 0x100
	s_addc_u32 s1, s1, 0
	s_add_u32 s81, s81, 0x100
	s_addc_u32 s82, s82, 0
	s_cmp_gt_u32 s83, 13
	s_cbranch_scc0 .LBB0_668
	s_and_b64 vcc, exec, s[36:37]
	s_cbranch_vccnz .LBB0_680
	s_and_saveexec_b64 s[0:1], s[6:7]
	s_cbranch_execnz .LBB0_681

; #define PG8_STAGE(bufoff, gbase, voff) do { _Pragma("unroll") for (int _i = 0; _i < 2; ++_i) \
;         __builtin_amdgcn_global_load_lds((const unsigned*)((const char*)(gbase) + (voff)[_i]), (PG8_LAS unsigned*)(lds + (bufoff) + ldsw + _i * 8192), 16, 0, 0); } while (0)
; #define PG8_LDA(dst, b, h) do { _Pragma("unroll") for (int m = 0; m < 4; ++m) _Pragma("unroll") for (int k = 0; k < 2; ++k) dst[m][k] = *(const PG8_LAS bf16x8*)(lds + PG8_SA(b, h) + aoff + m * 2048 + k * 1024); } while (0)
; #define PG8_LDB(dst, b, h) do { _Pragma("unroll") for (int n = 0; n < 2; ++n) _Pragma("unroll") for (int k = 0; k < 2; ++k) dst[n][k] = *(const PG8_LAS bf16x8*)(lds + PG8_SB(b, h) + boff + n * 2048 + k * 1024); } while (0)
; #define PG8_MMA(ai, bj, At, Bt) do { __builtin_amdgcn_s_setprio(1); _Pragma("unroll") for (int m = 0; m < 4; ++m) _Pragma("unroll") for (int n = 0; n < 2; ++n) _Pragma("unroll") for (int k = 0; k < 2; ++k) \
;         acc[ai][bj][m][n] = __builtin_amdgcn_mfma_f32_16x16x32_bf16(Bt[n][k], At[m][k], acc[ai][bj][m][n], 0, 0, 0); __builtin_amdgcn_s_setprio(0); } while (0)
; #define PG8_WAIT_V(n) asm volatile("s_waitcnt vmcnt(" #n ")" ::: "memory")
; #define PG8_BAR __builtin_amdgcn_s_barrier()
; template <class Epi, class Sched, bool ALIGN_EPI = false, bool SP2 = false>
; __device__ __forceinline__ void gemm_phase(PG8_LAS unsigned char* lds, const Gemm g, const Sched& S, const Epi& E) {
;     ...
;         for (int t = 0; t < nt_u; t += 2) {
;             const bool last = (t == nt_u - 2);
;             const char* a1 = cA + (size_t)(t + 1) * kstep;
;             const char* a2 = last ? nA : cA + (size_t)(t + 2) * kstep; const char* b2 = last ? nB : cB + (size_t)(t + 2) * kstep;
;             const char* a3 = a2 + kstep; const char* b3 = b2 + kstep;
;             if (last && has_next) S.a_ready(nxt);
;             if constexpr (SP2) {
;             PG8_LDB(B0, 0, 0); PG8_LDB(B1, 0, 1); PG8_SCHED; PG8_LDA(At, 0, 0); PG8_STAGE(PG8_SA(1, 1), a1 + hstep, voffA);
;             PG8_WAIT_V(8); PG8_WAIT_L(0); PG8_BAR; PG8_MMA(0, 0, At, B0); PG8_MMA(0, 1, At, B1); PG8_BAR; PG8_SCHED;
;             PG8_LDA(At, 0, 1); PG8_STAGE(PG8_SB(0, 0), b2, voffB); PG8_STAGE(PG8_SB(0, 1), b2 + hstep, voffB); PG8_STAGE(PG8_SA(0, 0), a2, voffA);
;             PG8_WAIT_V(8); PG8_WAIT_L(0); PG8_BAR; PG8_MMA(1, 0, At, B0); PG8_MMA(1, 1, At, B1); PG8_BAR; PG8_SCHED;
.LBB0_822:
	ds_read_b128 v[64:67], v161
	ds_read_b128 v[108:111], v161 offset:1024
	ds_read_b128 v[112:115], v161 offset:2048
	ds_read_b128 v[120:123], v161 offset:3072
	ds_read_b128 v[154:157], v162
	ds_read_b128 v[164:167], v162 offset:1024
	ds_read_b128 v[168:171], v162 offset:2048
	ds_read_b128 v[172:175], v162 offset:3072
	s_add_i32 s69, s36, 2
	s_add_u32 s30, s28, 0x100
	s_addc_u32 s31, s29, 0
	s_cmp_eq_u32 s12, s36
	s_cselect_b32 s36, s26, s13
	s_cselect_b32 s39, s25, s31
	s_cselect_b32 s38, s24, s30
	s_cselect_b32 s37, s27, s23
	v_lshl_add_u64 v[210:211], s[28:29], 0, v[148:149]
	s_add_i32 m0, s41, 0xc000
	ds_read_b128 v[178:181], v163
	ds_read_b128 v[182:185], v163 offset:1024
	ds_read_b128 v[186:189], v163 offset:2048
	ds_read_b128 v[190:193], v163 offset:3072
	ds_read_b128 v[194:197], v163 offset:4096
	ds_read_b128 v[198:201], v163 offset:5120
	ds_read_b128 v[202:205], v163 offset:6144
	ds_read_b128 v[206:209], v163 offset:7168
	global_load_lds_dwordx4 v[210:211], off
	v_lshl_add_u64 v[210:211], s[28:29], 0, v[150:151]
	s_add_i32 m0, s41, 0xe000
	s_nop 0
	global_load_lds_dwordx4 v[210:211], off
	s_waitcnt vmcnt(8)
	s_waitcnt lgkmcnt(0)
	s_barrier
	s_waitcnt lgkmcnt(0)
	v_mfma_f32_16x16x32_bf16 v[140:143], v[64:67], v[178:181], v[140:143]
	v_mfma_f32_16x16x32_bf16 v[136:139], v[112:115], v[178:181], v[136:139]
	v_mfma_f32_16x16x32_bf16 v[124:127], v[64:67], v[186:189], v[124:127]
	v_mfma_f32_16x16x32_bf16 v[116:119], v[112:115], v[186:189], v[116:119]
	v_mfma_f32_16x16x32_bf16 v[96:99], v[64:67], v[194:197], v[96:99]
	v_mfma_f32_16x16x32_bf16 v[92:95], v[112:115], v[194:197], v[92:95]
	v_mfma_f32_16x16x32_bf16 v[80:83], v[64:67], v[202:205], v[80:83]
	v_mfma_f32_16x16x32_bf16 v[76:79], v[112:115], v[202:205], v[76:79]
	v_mfma_f32_16x16x32_bf16 v[140:143], v[108:111], v[182:185], v[140:143]
	v_mfma_f32_16x16x32_bf16 v[136:139], v[120:123], v[182:185], v[136:139]
	v_mfma_f32_16x16x32_bf16 v[124:127], v[108:111], v[190:193], v[124:127]
	v_mfma_f32_16x16x32_bf16 v[116:119], v[120:123], v[190:193], v[116:119]
	v_mfma_f32_16x16x32_bf16 v[96:99], v[108:111], v[198:201], v[96:99]
	v_mfma_f32_16x16x32_bf16 v[92:95], v[120:123], v[198:201], v[92:95]
	v_mfma_f32_16x16x32_bf16 v[80:83], v[108:111], v[206:209], v[80:83]
	v_mfma_f32_16x16x32_bf16 v[76:79], v[120:123], v[206:209], v[76:79]
	v_mfma_f32_16x16x32_bf16 v[132:135], v[154:157], v[178:181], v[132:135]
	v_mfma_f32_16x16x32_bf16 v[128:131], v[168:171], v[178:181], v[128:131]
	v_mfma_f32_16x16x32_bf16 v[104:107], v[154:157], v[186:189], v[104:107]
	v_mfma_f32_16x16x32_bf16 v[100:103], v[168:171], v[186:189], v[100:103]
	v_mfma_f32_16x16x32_bf16 v[88:91], v[154:157], v[194:197], v[88:91]
	v_mfma_f32_16x16x32_bf16 v[84:87], v[168:171], v[194:197], v[84:87]
	v_mfma_f32_16x16x32_bf16 v[72:75], v[154:157], v[202:205], v[72:75]
	v_mfma_f32_16x16x32_bf16 v[68:71], v[168:171], v[202:205], v[68:71]
	v_mfma_f32_16x16x32_bf16 v[132:135], v[164:167], v[182:185], v[132:135]
	v_mfma_f32_16x16x32_bf16 v[128:131], v[172:175], v[182:185], v[128:131]
	v_mfma_f32_16x16x32_bf16 v[104:107], v[164:167], v[190:193], v[104:107]
	v_mfma_f32_16x16x32_bf16 v[100:103], v[172:175], v[190:193], v[100:103]
	v_mfma_f32_16x16x32_bf16 v[88:91], v[164:167], v[198:201], v[88:91]
	v_mfma_f32_16x16x32_bf16 v[84:87], v[172:175], v[198:201], v[84:87]
	v_mfma_f32_16x16x32_bf16 v[72:75], v[164:167], v[206:209], v[72:75]
	v_mfma_f32_16x16x32_bf16 v[68:71], v[172:175], v[206:209], v[68:71]
	s_barrier
	s_add_i32 s20, s60, s3
	v_lshl_add_u64 v[210:211], s[36:37], 0, v[146:147]
	s_mov_b32 m0, s20
	ds_read_b128 v[178:181], v163 offset:16384
	ds_read_b128 v[182:185], v163 offset:17408
	ds_read_b128 v[186:189], v163 offset:18432
	ds_read_b128 v[190:193], v163 offset:19456
	ds_read_b128 v[194:197], v163 offset:20480
	ds_read_b128 v[198:201], v163 offset:21504
	ds_read_b128 v[202:205], v163 offset:22528
	ds_read_b128 v[206:209], v163 offset:23552
	global_load_lds_dwordx4 v[210:211], off
	s_add_i32 m0, s20, 0x2000
	s_add_u32 s20, s36, 0xb0000
	v_lshl_add_u64 v[212:213], s[36:37], 0, v[144:145]
	s_addc_u32 s21, s37, 0
	s_add_i32 s28, s61, s3
	global_load_lds_dwordx4 v[212:213], off
	v_lshl_add_u64 v[214:215], s[20:21], 0, v[146:147]
	s_mov_b32 m0, s28
	v_lshl_add_u64 v[216:217], s[38:39], 0, v[144:145]
	global_load_lds_dwordx4 v[214:215], off
	v_lshl_add_u64 v[214:215], s[20:21], 0, v[144:145]
	s_add_i32 m0, s28, 0x2000
	s_nop 0
	global_load_lds_dwordx4 v[214:215], off
	v_lshl_add_u64 v[214:215], s[38:39], 0, v[146:147]
	s_mov_b32 m0, s41
	s_nop 0
	global_load_lds_dwordx4 v[214:215], off
	s_mov_b32 m0, s42
	s_nop 0
	global_load_lds_dwordx4 v[216:217], off
	s_waitcnt vmcnt(8)
	s_waitcnt lgkmcnt(0)
	s_barrier
; #define PG8_STAGE(bufoff, gbase, voff) do { _Pragma("unroll") for (int _i = 0; _i < 2; ++_i) \
;         __builtin_amdgcn_global_load_lds((const unsigned*)((const char*)(gbase) + (voff)[_i]), (PG8_LAS unsigned*)(lds + (bufoff) + ldsw + _i * 8192), 16, 0, 0); } while (0)
; #define PG8_LDA(dst, b, h) do { _Pragma("unroll") for (int m = 0; m < 4; ++m) _Pragma("unroll") for (int k = 0; k < 2; ++k) dst[m][k] = *(const PG8_LAS bf16x8*)(lds + PG8_SA(b, h) + aoff + m * 2048 + k * 1024); } while (0)
; #define PG8_LDB(dst, b, h) do { _Pragma("unroll") for (int n = 0; n < 2; ++n) _Pragma("unroll") for (int k = 0; k < 2; ++k) dst[n][k] = *(const PG8_LAS bf16x8*)(lds + PG8_SB(b, h) + boff + n * 2048 + k * 1024); } while (0)
; #define PG8_MMA(ai, bj, At, Bt) do { __builtin_amdgcn_s_setprio(1); _Pragma("unroll") for (int m = 0; m < 4; ++m) _Pragma("unroll") for (int n = 0; n < 2; ++n) _Pragma("unroll") for (int k = 0; k < 2; ++k) \
;         acc[ai][bj][m][n] = __builtin_amdgcn_mfma_f32_16x16x32_bf16(Bt[n][k], At[m][k], acc[ai][bj][m][n], 0, 0, 0); __builtin_amdgcn_s_setprio(0); } while (0)
; #define PG8_WAIT_V(n) asm volatile("s_waitcnt vmcnt(" #n ")" ::: "memory")
; #define PG8_WAIT_L(n) asm volatile("s_waitcnt lgkmcnt(" #n ")" ::: "memory")
; #define PG8_BAR __builtin_amdgcn_s_barrier()
; #define PG8_SCHED __builtin_amdgcn_sched_barrier(0)
; template <class Epi, class Sched, bool ALIGN_EPI = false, bool SP2 = false>
; __device__ __forceinline__ void gemm_phase(PG8_LAS unsigned char* lds, const Gemm g, const Sched& S, const Epi& E) {
;     ...
;             PG8_WAIT_V(8); PG8_WAIT_L(0); PG8_BAR; PG8_MMA(1, 0, At, B0); PG8_MMA(1, 1, At, B1); PG8_BAR; PG8_SCHED;
;             PG8_LDB(B0, 1, 0); PG8_LDB(B1, 1, 1); PG8_SCHED; PG8_LDA(At, 1, 0); PG8_STAGE(PG8_SA(0, 1), a2 + hstep, voffA);
;             PG8_WAIT_V(8); PG8_WAIT_L(0); PG8_BAR; PG8_MMA(0, 0, At, B0); PG8_MMA(0, 1, At, B1); PG8_BAR; PG8_SCHED;
	s_waitcnt lgkmcnt(0)
	v_mfma_f32_16x16x32_bf16 v[60:63], v[64:67], v[178:181], v[60:63]
	v_mfma_f32_16x16x32_bf16 v[56:59], v[112:115], v[178:181], v[56:59]
	v_mfma_f32_16x16x32_bf16 v[44:47], v[64:67], v[186:189], v[44:47]
	v_mfma_f32_16x16x32_bf16 v[40:43], v[112:115], v[186:189], v[40:43]
	v_mfma_f32_16x16x32_bf16 v[28:31], v[64:67], v[194:197], v[28:31]
	v_mfma_f32_16x16x32_bf16 v[24:27], v[112:115], v[194:197], v[24:27]
	v_mfma_f32_16x16x32_bf16 v[16:19], v[64:67], v[202:205], v[16:19]
	v_mfma_f32_16x16x32_bf16 v[8:11], v[112:115], v[202:205], v[8:11]
	v_mfma_f32_16x16x32_bf16 v[60:63], v[108:111], v[182:185], v[60:63]
	v_mfma_f32_16x16x32_bf16 v[56:59], v[120:123], v[182:185], v[56:59]
	v_mfma_f32_16x16x32_bf16 v[44:47], v[108:111], v[190:193], v[44:47]
	v_mfma_f32_16x16x32_bf16 v[40:43], v[120:123], v[190:193], v[40:43]
	v_mfma_f32_16x16x32_bf16 v[28:31], v[108:111], v[198:201], v[28:31]
	v_mfma_f32_16x16x32_bf16 v[24:27], v[120:123], v[198:201], v[24:27]
	v_mfma_f32_16x16x32_bf16 v[16:19], v[108:111], v[206:209], v[16:19]
	v_mfma_f32_16x16x32_bf16 v[8:11], v[120:123], v[206:209], v[8:11]
	v_mfma_f32_16x16x32_bf16 v[52:55], v[154:157], v[178:181], v[52:55]
	v_mfma_f32_16x16x32_bf16 v[48:51], v[168:171], v[178:181], v[48:51]
	v_mfma_f32_16x16x32_bf16 v[36:39], v[154:157], v[186:189], v[36:39]
	v_mfma_f32_16x16x32_bf16 v[32:35], v[168:171], v[186:189], v[32:35]
	v_mfma_f32_16x16x32_bf16 v[20:23], v[154:157], v[194:197], v[20:23]
	v_mfma_f32_16x16x32_bf16 v[12:15], v[168:171], v[194:197], v[12:15]
	v_mfma_f32_16x16x32_bf16 v[4:7], v[154:157], v[202:205], v[4:7]
	v_mfma_f32_16x16x32_bf16 v[0:3], v[168:171], v[202:205], v[0:3]
	v_mfma_f32_16x16x32_bf16 v[52:55], v[164:167], v[182:185], v[52:55]
	v_mfma_f32_16x16x32_bf16 v[48:51], v[172:175], v[182:185], v[48:51]
	v_mfma_f32_16x16x32_bf16 v[36:39], v[164:167], v[190:193], v[36:39]
	v_mfma_f32_16x16x32_bf16 v[32:35], v[172:175], v[190:193], v[32:35]
	v_mfma_f32_16x16x32_bf16 v[20:23], v[164:167], v[198:201], v[20:23]
	v_mfma_f32_16x16x32_bf16 v[12:15], v[172:175], v[198:201], v[12:15]
	v_mfma_f32_16x16x32_bf16 v[4:7], v[164:167], v[206:209], v[4:7]
	v_mfma_f32_16x16x32_bf16 v[0:3], v[172:175], v[206:209], v[0:3]
	s_barrier
	s_add_i32 s28, 0, 0x18000
	s_add_i32 s29, 0, 0x1c000
	v_add_u32_e32 v120, s28, v159
	v_add_u32_e32 v172, s29, v159
	ds_read_b128 v[64:67], v120
	ds_read_b128 v[108:111], v120 offset:1024
	ds_read_b128 v[112:115], v120 offset:2048
	ds_read_b128 v[120:123], v120 offset:3072
	ds_read_b128 v[154:157], v172
	ds_read_b128 v[164:167], v172 offset:1024
	ds_read_b128 v[168:171], v172 offset:2048
	ds_read_b128 v[172:175], v172 offset:3072
	s_add_u32 s20, s38, 0xb0000
	s_addc_u32 s21, s39, 0
	s_mov_b32 m0, s43
	v_lshl_add_u64 v[218:219], s[20:21], 0, v[146:147]
	ds_read_b128 v[178:181], v163 offset:32768
	ds_read_b128 v[182:185], v163 offset:33792
	ds_read_b128 v[186:189], v163 offset:34816
	ds_read_b128 v[190:193], v163 offset:35840
	ds_read_b128 v[194:197], v163 offset:36864
	ds_read_b128 v[198:201], v163 offset:37888
	ds_read_b128 v[202:205], v163 offset:38912
	ds_read_b128 v[206:209], v163 offset:39936
	global_load_lds_dwordx4 v[218:219], off
	v_lshl_add_u64 v[218:219], s[20:21], 0, v[144:145]
	s_mov_b32 m0, s44
	s_nop 0
	global_load_lds_dwordx4 v[218:219], off
	s_waitcnt vmcnt(8)
	s_waitcnt lgkmcnt(0)
	s_barrier
	s_waitcnt lgkmcnt(0)
	v_mfma_f32_16x16x32_bf16 v[140:143], v[64:67], v[178:181], v[140:143]
	v_mfma_f32_16x16x32_bf16 v[136:139], v[112:115], v[178:181], v[136:139]
	v_mfma_f32_16x16x32_bf16 v[124:127], v[64:67], v[186:189], v[124:127]
	v_mfma_f32_16x16x32_bf16 v[116:119], v[112:115], v[186:189], v[116:119]
	v_mfma_f32_16x16x32_bf16 v[96:99], v[64:67], v[194:197], v[96:99]
	v_mfma_f32_16x16x32_bf16 v[92:95], v[112:115], v[194:197], v[92:95]
	v_mfma_f32_16x16x32_bf16 v[80:83], v[64:67], v[202:205], v[80:83]
	v_mfma_f32_16x16x32_bf16 v[76:79], v[112:115], v[202:205], v[76:79]
	v_mfma_f32_16x16x32_bf16 v[140:143], v[108:111], v[182:185], v[140:143]
	v_mfma_f32_16x16x32_bf16 v[136:139], v[120:123], v[182:185], v[136:139]
	v_mfma_f32_16x16x32_bf16 v[124:127], v[108:111], v[190:193], v[124:127]
	v_mfma_f32_16x16x32_bf16 v[116:119], v[120:123], v[190:193], v[116:119]
	v_mfma_f32_16x16x32_bf16 v[96:99], v[108:111], v[198:201], v[96:99]
	v_mfma_f32_16x16x32_bf16 v[92:95], v[120:123], v[198:201], v[92:95]
	v_mfma_f32_16x16x32_bf16 v[80:83], v[108:111], v[206:209], v[80:83]
	v_mfma_f32_16x16x32_bf16 v[76:79], v[120:123], v[206:209], v[76:79]
	v_mfma_f32_16x16x32_bf16 v[132:135], v[154:157], v[178:181], v[132:135]
	v_mfma_f32_16x16x32_bf16 v[128:131], v[168:171], v[178:181], v[128:131]
	v_mfma_f32_16x16x32_bf16 v[104:107], v[154:157], v[186:189], v[104:107]
	v_mfma_f32_16x16x32_bf16 v[100:103], v[168:171], v[186:189], v[100:103]
	v_mfma_f32_16x16x32_bf16 v[88:91], v[154:157], v[194:197], v[88:91]
	v_mfma_f32_16x16x32_bf16 v[84:87], v[168:171], v[194:197], v[84:87]
	v_mfma_f32_16x16x32_bf16 v[72:75], v[154:157], v[202:205], v[72:75]
	v_mfma_f32_16x16x32_bf16 v[68:71], v[168:171], v[202:205], v[68:71]
	v_mfma_f32_16x16x32_bf16 v[132:135], v[164:167], v[182:185], v[132:135]
	v_mfma_f32_16x16x32_bf16 v[128:131], v[172:175], v[182:185], v[128:131]
	v_mfma_f32_16x16x32_bf16 v[104:107], v[164:167], v[190:193], v[104:107]
	v_mfma_f32_16x16x32_bf16 v[100:103], v[172:175], v[190:193], v[100:103]
	v_mfma_f32_16x16x32_bf16 v[88:91], v[164:167], v[198:201], v[88:91]
	v_mfma_f32_16x16x32_bf16 v[84:87], v[172:175], v[198:201], v[84:87]
	v_mfma_f32_16x16x32_bf16 v[72:75], v[164:167], v[206:209], v[72:75]
	v_mfma_f32_16x16x32_bf16 v[68:71], v[172:175], v[206:209], v[68:71]
	s_barrier
; #define PG8_STAGE(bufoff, gbase, voff) do { _Pragma("unroll") for (int _i = 0; _i < 2; ++_i) \
;         __builtin_amdgcn_global_load_lds((const unsigned*)((const char*)(gbase) + (voff)[_i]), (PG8_LAS unsigned*)(lds + (bufoff) + ldsw + _i * 8192), 16, 0, 0); } while (0)
; #define PG8_LDA(dst, b, h) do { _Pragma("unroll") for (int m = 0; m < 4; ++m) _Pragma("unroll") for (int k = 0; k < 2; ++k) dst[m][k] = *(const PG8_LAS bf16x8*)(lds + PG8_SA(b, h) + aoff + m * 2048 + k * 1024); } while (0)
; #define PG8_MMA(ai, bj, At, Bt) do { __builtin_amdgcn_s_setprio(1); _Pragma("unroll") for (int m = 0; m < 4; ++m) _Pragma("unroll") for (int n = 0; n < 2; ++n) _Pragma("unroll") for (int k = 0; k < 2; ++k) \
;         acc[ai][bj][m][n] = __builtin_amdgcn_mfma_f32_16x16x32_bf16(Bt[n][k], At[m][k], acc[ai][bj][m][n], 0, 0, 0); __builtin_amdgcn_s_setprio(0); } while (0)
; #define PG8_WAIT_V(n) asm volatile("s_waitcnt vmcnt(" #n ")" ::: "memory")
; #define PG8_WAIT_L(n) asm volatile("s_waitcnt lgkmcnt(" #n ")" ::: "memory")
; #define PG8_BAR __builtin_amdgcn_s_barrier()
; #define PG8_SCHED __builtin_amdgcn_sched_barrier(0)
; template <class Epi, class Sched, bool ALIGN_EPI = false, bool SP2 = false>
; __device__ __forceinline__ void gemm_phase(PG8_LAS unsigned char* lds, const Gemm g, const Sched& S, const Epi& E) {
;     ...
;             PG8_LDA(At, 1, 1); PG8_STAGE(PG8_SB(1, 0), b3, voffB); PG8_STAGE(PG8_SB(1, 1), b3 + hstep, voffB); PG8_STAGE(PG8_SA(1, 0), a3, voffA);
;             PG8_WAIT_V(8); PG8_WAIT_L(0); PG8_BAR; PG8_MMA(1, 0, At, B0); PG8_MMA(1, 1, At, B1); PG8_BAR; PG8_SCHED;
	s_add_i32 s20, s28, s3
	v_lshl_add_u64 v[210:211], v[210:211], 0, s[8:9]
	s_mov_b32 m0, s20
	ds_read_b128 v[178:181], v163 offset:49152
	ds_read_b128 v[182:185], v163 offset:50176
	ds_read_b128 v[186:189], v163 offset:51200
	ds_read_b128 v[190:193], v163 offset:52224
	ds_read_b128 v[194:197], v163 offset:53248
	ds_read_b128 v[198:201], v163 offset:54272
	ds_read_b128 v[202:205], v163 offset:55296
	ds_read_b128 v[206:209], v163 offset:56320
	global_load_lds_dwordx4 v[210:211], off
	s_add_i32 m0, s20, 0x2000
	s_add_u32 s20, s36, 0xb0080
	v_lshl_add_u64 v[210:211], v[212:213], 0, s[8:9]
	s_addc_u32 s21, s37, 0
	s_add_i32 s28, s29, s3
	global_load_lds_dwordx4 v[210:211], off
	v_lshl_add_u64 v[210:211], s[20:21], 0, v[146:147]
	s_mov_b32 m0, s28
	s_nop 0
	global_load_lds_dwordx4 v[210:211], off
	v_lshl_add_u64 v[210:211], s[20:21], 0, v[144:145]
	s_add_i32 m0, s28, 0x2000
	s_nop 0
	global_load_lds_dwordx4 v[210:211], off
	v_lshl_add_u64 v[210:211], v[214:215], 0, s[8:9]
	s_mov_b32 m0, s46
	s_nop 0
	global_load_lds_dwordx4 v[210:211], off
	v_lshl_add_u64 v[210:211], v[216:217], 0, s[8:9]
	s_mov_b32 m0, s47
	s_nop 0
	global_load_lds_dwordx4 v[210:211], off
	s_waitcnt vmcnt(8)
	s_waitcnt lgkmcnt(0)
	s_barrier
	s_waitcnt lgkmcnt(0)
	v_mfma_f32_16x16x32_bf16 v[60:63], v[64:67], v[178:181], v[60:63]
	v_mfma_f32_16x16x32_bf16 v[56:59], v[112:115], v[178:181], v[56:59]
	v_mfma_f32_16x16x32_bf16 v[44:47], v[64:67], v[186:189], v[44:47]
	v_mfma_f32_16x16x32_bf16 v[40:43], v[112:115], v[186:189], v[40:43]
	v_mfma_f32_16x16x32_bf16 v[28:31], v[64:67], v[194:197], v[28:31]
	v_mfma_f32_16x16x32_bf16 v[24:27], v[112:115], v[194:197], v[24:27]
	v_mfma_f32_16x16x32_bf16 v[16:19], v[64:67], v[202:205], v[16:19]
	v_mfma_f32_16x16x32_bf16 v[8:11], v[112:115], v[202:205], v[8:11]
	v_mfma_f32_16x16x32_bf16 v[60:63], v[108:111], v[182:185], v[60:63]
	v_mfma_f32_16x16x32_bf16 v[56:59], v[120:123], v[182:185], v[56:59]
	v_mfma_f32_16x16x32_bf16 v[44:47], v[108:111], v[190:193], v[44:47]
	v_mfma_f32_16x16x32_bf16 v[40:43], v[120:123], v[190:193], v[40:43]
	v_mfma_f32_16x16x32_bf16 v[28:31], v[108:111], v[198:201], v[28:31]
	v_mfma_f32_16x16x32_bf16 v[24:27], v[120:123], v[198:201], v[24:27]
	v_mfma_f32_16x16x32_bf16 v[16:19], v[108:111], v[206:209], v[16:19]
	v_mfma_f32_16x16x32_bf16 v[8:11], v[120:123], v[206:209], v[8:11]
	v_mfma_f32_16x16x32_bf16 v[52:55], v[154:157], v[178:181], v[52:55]
	v_mfma_f32_16x16x32_bf16 v[48:51], v[168:171], v[178:181], v[48:51]
	v_mfma_f32_16x16x32_bf16 v[36:39], v[154:157], v[186:189], v[36:39]
	v_mfma_f32_16x16x32_bf16 v[32:35], v[168:171], v[186:189], v[32:35]
	v_mfma_f32_16x16x32_bf16 v[20:23], v[154:157], v[194:197], v[20:23]
	v_mfma_f32_16x16x32_bf16 v[12:15], v[168:171], v[194:197], v[12:15]
	v_mfma_f32_16x16x32_bf16 v[4:7], v[154:157], v[202:205], v[4:7]
	v_mfma_f32_16x16x32_bf16 v[0:3], v[168:171], v[202:205], v[0:3]
	v_mfma_f32_16x16x32_bf16 v[52:55], v[164:167], v[182:185], v[52:55]
	v_mfma_f32_16x16x32_bf16 v[48:51], v[172:175], v[182:185], v[48:51]
	v_mfma_f32_16x16x32_bf16 v[36:39], v[164:167], v[190:193], v[36:39]
	v_mfma_f32_16x16x32_bf16 v[32:35], v[172:175], v[190:193], v[32:35]
	v_mfma_f32_16x16x32_bf16 v[20:23], v[164:167], v[198:201], v[20:23]
	v_mfma_f32_16x16x32_bf16 v[12:15], v[172:175], v[198:201], v[12:15]
	v_mfma_f32_16x16x32_bf16 v[4:7], v[164:167], v[206:209], v[4:7]
	v_mfma_f32_16x16x32_bf16 v[0:3], v[172:175], v[206:209], v[0:3]
	s_barrier
	s_add_u32 s13, s13, 0x100
	s_addc_u32 s23, s23, 0
	s_cmp_ge_i32 s69, s67
	s_mov_b64 s[28:29], s[30:31]
	s_mov_b32 s36, s69
	s_cbranch_scc0 .LBB0_822
	s_and_b64 vcc, exec, s[10:11]
	s_cbranch_vccz .LBB0_825
	s_barrier
